# batch: mem-attention counted vmcnt, FoX prologue load prefetch, skip dead bf16-copy stores and ssq atomics in the last layer out-proj
# speedup vs baseline: 1.0314x; 1.0065x over previous
.LBB0_851:
	v_readlane_b32 s0, v252, 46
	v_readlane_b32 s1, v252, 47
	s_and_b64 vcc, exec, s[0:1]
	s_cbranch_vccz .LBB0_882
	v_readlane_b32 s0, v252, 48
	v_readlane_b32 s1, v252, 49
	v_mov_b32_e32 v0, v198
	s_andn2_b64 vcc, exec, s[0:1]
	s_cbranch_vccnz .LBB0_882
	v_ashrrev_i32_e32 v2, 1, v0
	s_movk_i32 s0, 0xffe0
	v_bfi_b32 v2, s0, v2, v0
	v_readlane_b32 s0, v253, 6
	v_lshrrev_b32_e32 v0, 1, v0
	v_and_b32_e32 v0, 16, v0
	v_add_u32_e32 v4, s0, v2
	v_readlane_b32 s0, v253, 8
	v_readlane_b32 s1, v253, 9
	v_readlane_b32 s6, v253, 10
	v_readlane_b32 s7, v253, 11
	v_mov_b64_e32 v[2:3], s[0:1]
	s_movk_i32 s0, 0x2200
	v_mad_i64_i32 v[2:3], s[0:1], v4, s0, v[2:3]
	v_lshl_add_u64 v[30:31], v[2:3], 0, v[0:1]
	global_load_dwordx4 v[2:5], v[30:31], off
	global_load_dwordx4 v[6:9], v[30:31], off offset:32
	global_load_dwordx4 v[10:13], v[30:31], off offset:64
	global_load_dwordx4 v[14:17], v[30:31], off offset:96
	global_load_dwordx4 v[18:21], v[30:31], off offset:128
	global_load_dwordx4 v[22:25], v[30:31], off offset:160
	global_load_dwordx4 v[26:29], v[30:31], off offset:192
	s_nop 0
	global_load_dwordx4 v[30:33], v[30:31], off offset:224
	v_mov_b32_e32 v149, v1
	s_mov_b64 s[10:11], 0x400
	s_mov_b64 s[16:17], 0x480
	s_mov_b32 s15, 0
	v_mov_b32_e32 v153, 0
	v_mov_b32_e32 v156, 0xf149f2ca
	s_mov_b32 s18, 0
	s_waitcnt vmcnt(0)
	v_lshlrev_b32_e32 v0, 16, v2
	v_and_b32_e32 v2, 0xffff0000, v2
	v_lshlrev_b32_e32 v34, 16, v3
	v_and_b32_e32 v3, 0xffff0000, v3
	v_lshlrev_b32_e32 v39, 16, v8
	v_and_b32_e32 v8, 0xffff0000, v8
	v_mul_f32_e32 v2, 0x3e0293ee, v2
	v_mul_f32_e32 v3, 0x3e0293ee, v3
	v_lshlrev_b32_e32 v35, 16, v4
	v_and_b32_e32 v4, 0xffff0000, v4
	v_lshlrev_b32_e32 v36, 16, v5
	v_and_b32_e32 v5, 0xffff0000, v5
	v_lshlrev_b32_e32 v37, 16, v6
	v_and_b32_e32 v6, 0xffff0000, v6
	v_lshlrev_b32_e32 v38, 16, v7
	v_and_b32_e32 v7, 0xffff0000, v7
	v_lshlrev_b32_e32 v47, 16, v16
	v_and_b32_e32 v16, 0xffff0000, v16
	v_mul_f32_e32 v0, 0x3e0293ee, v0
	v_mul_f32_e32 v34, 0x3e0293ee, v34
	v_mul_f32_e32 v8, 0x3e0293ee, v8
	v_cvt_pk_bf16_f32 v112, v0, v2
	v_cvt_pk_bf16_f32 v113, v34, v3
	v_lshlrev_b32_e32 v2, 16, v17
	v_and_b32_e32 v3, 0xffff0000, v17
	v_lshlrev_b32_e32 v40, 16, v9
	v_and_b32_e32 v9, 0xffff0000, v9
	v_lshlrev_b32_e32 v41, 16, v10
	v_and_b32_e32 v10, 0xffff0000, v10
	v_lshlrev_b32_e32 v42, 16, v11
	v_and_b32_e32 v11, 0xffff0000, v11
	v_lshlrev_b32_e32 v43, 16, v12
	v_and_b32_e32 v12, 0xffff0000, v12
	v_lshlrev_b32_e32 v44, 16, v13
	v_and_b32_e32 v13, 0xffff0000, v13
	v_lshlrev_b32_e32 v45, 16, v14
	v_and_b32_e32 v14, 0xffff0000, v14
	v_lshlrev_b32_e32 v46, 16, v15
	v_and_b32_e32 v15, 0xffff0000, v15
	v_mul_f32_e32 v35, 0x3e0293ee, v35
	v_mul_f32_e32 v4, 0x3e0293ee, v4
	v_mul_f32_e32 v36, 0x3e0293ee, v36
	v_mul_f32_e32 v5, 0x3e0293ee, v5
	v_mul_f32_e32 v37, 0x3e0293ee, v37
	v_mul_f32_e32 v6, 0x3e0293ee, v6
	v_mul_f32_e32 v38, 0x3e0293ee, v38
	v_mul_f32_e32 v7, 0x3e0293ee, v7
	v_mul_f32_e32 v39, 0x3e0293ee, v39
	v_cvt_pk_bf16_f32 v114, v35, v4
	v_cvt_pk_bf16_f32 v115, v36, v5
	v_cvt_pk_bf16_f32 v116, v37, v6
	v_cvt_pk_bf16_f32 v117, v38, v7
	v_cvt_pk_bf16_f32 v118, v39, v8
	v_mul_f32_e32 v0, 0x3e0293ee, v16
	v_mul_f32_e32 v2, 0x3e0293ee, v2
	v_mul_f32_e32 v3, 0x3e0293ee, v3
	v_and_b32_e32 v8, 0xffff0000, v21
	v_mul_f32_e32 v40, 0x3e0293ee, v40
	v_mul_f32_e32 v9, 0x3e0293ee, v9
	v_mul_f32_e32 v41, 0x3e0293ee, v41
	v_mul_f32_e32 v10, 0x3e0293ee, v10
	v_mul_f32_e32 v42, 0x3e0293ee, v42
	v_mul_f32_e32 v11, 0x3e0293ee, v11
	v_mul_f32_e32 v43, 0x3e0293ee, v43
	v_mul_f32_e32 v12, 0x3e0293ee, v12
	v_mul_f32_e32 v44, 0x3e0293ee, v44
	v_mul_f32_e32 v13, 0x3e0293ee, v13
	v_mul_f32_e32 v45, 0x3e0293ee, v45
	v_mul_f32_e32 v14, 0x3e0293ee, v14
	v_mul_f32_e32 v46, 0x3e0293ee, v46
	v_mul_f32_e32 v15, 0x3e0293ee, v15
	v_mul_f32_e32 v47, 0x3e0293ee, v47
	v_cvt_pk_bf16_f32 v119, v40, v9
	v_cvt_pk_bf16_f32 v120, v41, v10
	v_cvt_pk_bf16_f32 v121, v42, v11
	v_cvt_pk_bf16_f32 v122, v43, v12
	v_cvt_pk_bf16_f32 v123, v44, v13
	v_cvt_pk_bf16_f32 v124, v45, v14
	v_cvt_pk_bf16_f32 v125, v46, v15
	v_cvt_pk_bf16_f32 v126, v47, v0
	v_cvt_pk_bf16_f32 v127, v2, v3
	v_lshlrev_b32_e32 v0, 16, v18
	v_and_b32_e32 v2, 0xffff0000, v18
	v_lshlrev_b32_e32 v3, 16, v19
	v_and_b32_e32 v4, 0xffff0000, v19
	v_lshlrev_b32_e32 v5, 16, v20
	v_and_b32_e32 v6, 0xffff0000, v20
	v_lshlrev_b32_e32 v7, 16, v21
	v_mul_f32_e32 v8, 0x3e0293ee, v8
	v_mul_f32_e32 v0, 0x3e0293ee, v0
	v_mul_f32_e32 v2, 0x3e0293ee, v2
	v_mul_f32_e32 v3, 0x3e0293ee, v3
	v_mul_f32_e32 v4, 0x3e0293ee, v4
	v_mul_f32_e32 v5, 0x3e0293ee, v5
	v_mul_f32_e32 v6, 0x3e0293ee, v6
	v_mul_f32_e32 v7, 0x3e0293ee, v7
	v_cvt_pk_bf16_f32 v128, v0, v2
	v_cvt_pk_bf16_f32 v129, v3, v4
	v_cvt_pk_bf16_f32 v130, v5, v6
	v_cvt_pk_bf16_f32 v131, v7, v8
	v_and_b32_e32 v8, 0xffff0000, v25
	v_lshlrev_b32_e32 v0, 16, v22
	v_and_b32_e32 v2, 0xffff0000, v22
	v_lshlrev_b32_e32 v3, 16, v23
	v_and_b32_e32 v4, 0xffff0000, v23
	v_lshlrev_b32_e32 v5, 16, v24
	v_and_b32_e32 v6, 0xffff0000, v24
	v_lshlrev_b32_e32 v7, 16, v25
	v_mul_f32_e32 v8, 0x3e0293ee, v8
	v_mul_f32_e32 v0, 0x3e0293ee, v0
	v_mul_f32_e32 v2, 0x3e0293ee, v2
	v_mul_f32_e32 v3, 0x3e0293ee, v3
	v_mul_f32_e32 v4, 0x3e0293ee, v4
	v_mul_f32_e32 v5, 0x3e0293ee, v5
	v_mul_f32_e32 v6, 0x3e0293ee, v6
	v_mul_f32_e32 v7, 0x3e0293ee, v7
	v_cvt_pk_bf16_f32 v132, v0, v2
	v_cvt_pk_bf16_f32 v133, v3, v4
	v_cvt_pk_bf16_f32 v134, v5, v6
	v_cvt_pk_bf16_f32 v135, v7, v8
	v_and_b32_e32 v8, 0xffff0000, v29
	v_lshlrev_b32_e32 v0, 16, v26
	v_and_b32_e32 v2, 0xffff0000, v26
	v_lshlrev_b32_e32 v3, 16, v27
	v_and_b32_e32 v4, 0xffff0000, v27
	v_lshlrev_b32_e32 v5, 16, v28
	v_and_b32_e32 v6, 0xffff0000, v28
	v_lshlrev_b32_e32 v7, 16, v29
	v_mul_f32_e32 v8, 0x3e0293ee, v8
	v_mul_f32_e32 v0, 0x3e0293ee, v0
	v_mul_f32_e32 v2, 0x3e0293ee, v2
	v_mul_f32_e32 v3, 0x3e0293ee, v3
	v_mul_f32_e32 v4, 0x3e0293ee, v4
	v_mul_f32_e32 v5, 0x3e0293ee, v5
	v_mul_f32_e32 v6, 0x3e0293ee, v6
	v_mul_f32_e32 v7, 0x3e0293ee, v7
	v_cvt_pk_bf16_f32 v136, v0, v2
	v_cvt_pk_bf16_f32 v137, v3, v4
	v_cvt_pk_bf16_f32 v138, v5, v6
	v_cvt_pk_bf16_f32 v139, v7, v8
	v_and_b32_e32 v8, 0xffff0000, v33
	v_lshlrev_b32_e32 v0, 16, v30
	v_and_b32_e32 v2, 0xffff0000, v30
	v_lshlrev_b32_e32 v3, 16, v31
	v_and_b32_e32 v4, 0xffff0000, v31
	v_lshlrev_b32_e32 v5, 16, v32
	v_and_b32_e32 v6, 0xffff0000, v32
	v_lshlrev_b32_e32 v7, 16, v33
	v_mul_f32_e32 v8, 0x3e0293ee, v8
	v_mul_f32_e32 v0, 0x3e0293ee, v0
	v_mul_f32_e32 v2, 0x3e0293ee, v2
	v_mul_f32_e32 v3, 0x3e0293ee, v3
	v_mul_f32_e32 v4, 0x3e0293ee, v4
	v_mul_f32_e32 v5, 0x3e0293ee, v5
	v_mul_f32_e32 v6, 0x3e0293ee, v6
	v_mul_f32_e32 v7, 0x3e0293ee, v7
	v_cvt_pk_bf16_f32 v140, v0, v2
	v_cvt_pk_bf16_f32 v141, v3, v4
	v_cvt_pk_bf16_f32 v142, v5, v6
	v_cvt_pk_bf16_f32 v143, v7, v8
	v_mov_b32_e32 v8, v198
	v_mov_b32_e32 v14, v1
	v_readfirstlane_b32 s0, v8
	s_ashr_i32 s8, s0, 6
	v_lshrrev_b32_e32 v9, 1, v8
	s_lshl_b32 s0, s8, 3
	v_bfe_u32 v10, v8, 4, 2
	v_bfe_u32 v0, v8, 2, 3
	s_lshl_b32 s1, s8, 2
	v_lshlrev_b32_e32 v4, 3, v8
	v_bitop3_b32 v0, s0, v204, v0 bitop3:0xc8
	v_and_b32_e32 v3, 8, v9
	s_and_b32 s1, s1, 4
	v_and_b32_e32 v6, 24, v4
	v_bitop3_b32 v4, v10, v8, 15 bitop3:0x78
	v_and_b32_e32 v2, 15, v8
	v_or3_b32 v0, v3, v0, s1
	v_lshlrev_b32_e32 v11, 3, v4
	v_or_b32_e32 v4, 4, v10
	v_lshlrev_b32_e32 v7, 12, v0
	v_or_b32_e32 v0, s0, v10
	v_or_b32_e32 v4, s0, v4
	v_bitop3_b32 v2, v10, v2, 4 bitop3:0x36
	s_lshl_b32 s0, s8, 11
	s_add_i32 s1, 0, 0x10000
	v_and_b32_e32 v3, 32, v8
	v_lshl_or_b32 v0, v0, 12, v11
	v_lshlrev_b32_e32 v12, 3, v2
	s_add_i32 s2, s1, s0
	v_lshl_or_b32 v2, v4, 12, v12
	v_lshl_add_u64 v[4:5], v[0:1], 1, s[6:7]
	s_mov_b32 m0, s2
	v_or3_b32 v148, v3, v6, v7
	global_load_lds_dwordx4 v[4:5], off
	v_lshl_add_u64 v[4:5], v[148:149], 1, s[6:7]
	s_add_i32 s14, s0, 0
	v_lshl_add_u64 v[6:7], v[4:5], 0, s[10:11]
	s_mov_b32 m0, s14
	v_mov_b32_e32 v3, v1
	s_or_b32 s4, s0, 0x400
	global_load_lds_dwordx4 v[6:7], off
	v_lshl_add_u64 v[6:7], v[2:3], 1, s[6:7]
	s_add_i32 m0, s1, s4
	v_lshl_add_u64 v[4:5], v[4:5], 0, s[16:17]
	global_load_lds_dwordx4 v[6:7], off
	s_add_i32 m0, s14, 0x400
	v_add_u32_e32 v0, 0x40000, v0
	s_add_i32 s1, 0, 0x14000
	global_load_lds_dwordx4 v[4:5], off
	v_lshl_add_u64 v[4:5], v[0:1], 1, s[6:7]
	s_add_i32 m0, s1, s0
	v_add_u32_e32 v0, 0x40000, v148
	global_load_lds_dwordx4 v[4:5], off
	v_lshl_add_u64 v[4:5], v[0:1], 1, s[6:7]
	v_lshl_add_u64 v[4:5], v[4:5], 0, s[10:11]
	s_add_i32 m0, s14, 0x4000
	v_add_u32_e32 v0, 0x40000, v2
	global_load_lds_dwordx4 v[4:5], off
	v_lshl_add_u64 v[2:3], v[0:1], 1, s[6:7]
	s_add_i32 m0, s1, s4
	v_add_u32_e32 v0, 0x40040, v148
	global_load_lds_dwordx4 v[2:3], off
	v_lshl_add_u64 v[2:3], v[0:1], 1, s[6:7]
	v_lshl_add_u64 v[2:3], v[2:3], 0, s[10:11]
	s_add_i32 m0, s14, 0x4400
	v_and_b32_e32 v0, 63, v8
	global_load_lds_dwordx4 v[2:3], off
	v_and_b32_e32 v3, 0x3fffffc0, v8
	v_readlane_b32 s0, v254, 1
	v_lshlrev_b32_e32 v4, 4, v8
	v_and_b32_e32 v5, 0xc0, v4
	v_lshl_add_u32 v150, v3, 2, s0
	v_lshlrev_b32_e32 v3, 3, v0
	v_lshlrev_b32_e32 v6, 1, v8
	s_cmp_gt_i32 s8, 3
	v_and_or_b32 v5, v3, 24, v5
	v_and_b32_e32 v6, 32, v6
	v_and_b32_e32 v3, 0x100, v3
	s_cselect_b64 s[4:5], -1, 0
	s_cmp_lt_i32 s8, 4
	v_or3_b32 v149, v5, v6, v3
	v_and_b32_e32 v151, 16, v9
	v_and_b32_e32 v3, 0x70, v4
	s_movk_i32 s0, 0x60
	s_cselect_b64 s[6:7], -1, 0
	s_lshl_b32 s8, s8, 15
	v_and_b32_e32 v2, 31, v8
	v_bitop3_b32 v159, v151, v3, s0 bitop3:0x36
	s_waitcnt vmcnt(4)
	v_cmp_gt_u32_e64 s[0:1], 32, v0
	s_add_i32 s9, s8, 0x84000
	v_lshlrev_b32_e32 v0, 12, v10
	s_add_i32 s8, s8, 0x80000
	v_mov_b32_e32 v15, v1
	v_lshlrev_b32_e32 v154, 8, v2
	v_bitop3_b32 v155, v9, v3, 16 bitop3:0x6c
	v_bitop3_b32 v157, v151, v3, 32 bitop3:0x36
	v_bitop3_b32 v158, v151, v3, 64 bitop3:0x36
	v_lshl_add_u32 v152, v2, 2, v150
	v_or3_b32 v161, s9, v0, v12
	v_or3_b32 v162, s8, v0, v11
	v_mov_b32_e32 v0, v1
	v_mov_b32_e32 v2, v1
	v_mov_b32_e32 v3, v1
	v_mov_b32_e32 v4, v1
	v_mov_b32_e32 v5, v1
	v_mov_b32_e32 v6, v1
	v_mov_b32_e32 v7, v1
	v_mov_b32_e32 v8, v1
	v_mov_b32_e32 v9, v1
	v_mov_b32_e32 v10, v1
	v_mov_b32_e32 v11, v1
	v_mov_b32_e32 v12, v1
	v_mov_b32_e32 v13, v1
	v_mov_b64_e32 v[30:31], v[14:15]
	v_mov_b64_e32 v[46:47], v[14:15]
	v_mov_b64_e32 v[62:63], v[14:15]
	v_mov_b64_e32 v[78:79], v[14:15]
	v_mov_b64_e32 v[110:111], v[14:15]
	v_mov_b64_e32 v[94:95], v[14:15]
	v_add_u32_e32 v160, 0, v149
	s_mov_b64 s[10:11], 0
	v_mov_b64_e32 v[28:29], v[12:13]
	v_mov_b64_e32 v[26:27], v[10:11]
	v_mov_b64_e32 v[24:25], v[8:9]
	v_mov_b64_e32 v[22:23], v[6:7]
	v_mov_b64_e32 v[20:21], v[4:5]
	v_mov_b64_e32 v[18:19], v[2:3]
	v_mov_b64_e32 v[16:17], v[0:1]
	v_mov_b64_e32 v[44:45], v[12:13]
	v_mov_b64_e32 v[42:43], v[10:11]
	v_mov_b64_e32 v[40:41], v[8:9]
	v_mov_b64_e32 v[38:39], v[6:7]
	v_mov_b64_e32 v[36:37], v[4:5]
	v_mov_b64_e32 v[34:35], v[2:3]
	v_mov_b64_e32 v[32:33], v[0:1]
	v_mov_b64_e32 v[60:61], v[12:13]
	v_mov_b64_e32 v[58:59], v[10:11]
	v_mov_b64_e32 v[56:57], v[8:9]
	v_mov_b64_e32 v[54:55], v[6:7]
	v_mov_b64_e32 v[52:53], v[4:5]
	v_mov_b64_e32 v[50:51], v[2:3]
	v_mov_b64_e32 v[48:49], v[0:1]
	v_mov_b64_e32 v[76:77], v[12:13]
	v_mov_b64_e32 v[74:75], v[10:11]
	v_mov_b64_e32 v[72:73], v[8:9]
	v_mov_b64_e32 v[70:71], v[6:7]
	v_mov_b64_e32 v[68:69], v[4:5]
	v_mov_b64_e32 v[66:67], v[2:3]
	v_mov_b64_e32 v[64:65], v[0:1]
	s_mov_b32 s16, 0
	s_mov_b32 s17, 0
	v_mov_b64_e32 v[108:109], v[12:13]
	v_mov_b64_e32 v[106:107], v[10:11]
	v_mov_b64_e32 v[104:105], v[8:9]
	v_mov_b64_e32 v[102:103], v[6:7]
	v_mov_b64_e32 v[100:101], v[4:5]
	v_mov_b64_e32 v[98:99], v[2:3]
	v_mov_b64_e32 v[96:97], v[0:1]
	v_mov_b64_e32 v[92:93], v[12:13]
	v_mov_b64_e32 v[90:91], v[10:11]
	v_mov_b64_e32 v[88:89], v[8:9]
	v_mov_b64_e32 v[86:87], v[6:7]
	v_mov_b64_e32 v[84:85], v[4:5]
	v_mov_b64_e32 v[82:83], v[2:3]
	v_mov_b64_e32 v[80:81], v[0:1]
	s_waitcnt vmcnt(4) lgkmcnt(0)
	s_barrier
	s_cmp_gt_u32 s18, 1
	s_cselect_b64 s[8:9], -1, 0
	s_and_b64 vcc, exec, s[8:9]
	s_cbranch_vccnz .LBB0_855

.LBB0_869:
	s_add_i32 s8, s16, 1
	s_cmp_lg_u32 s16, 2
	s_cselect_b32 s16, s8, 0
	s_add_i32 s8, s17, 1
	s_and_b32 s17, s8, 3
	s_add_i32 s18, s18, 1
	s_add_i32 s15, s15, 0x40000
	s_cmp_eq_u32 s15, 0x100000
	s_waitcnt vmcnt(4)
	s_barrier
	s_cbranch_scc1 .LBB0_873
	s_mov_b64 s[10:11], s[4:5]
	s_cmp_gt_u32 s18, 1
	s_cselect_b64 s[8:9], -1, 0
	s_and_b64 vcc, exec, s[8:9]
	s_cbranch_vccz .LBB0_854
	s_branch .LBB0_855

.LBB0_1104:
	s_bfe_u32 s24, s48, 0x40002
	s_lshl_b32 s2, s24, 2
	v_mov_b32_e32 v4, s2
	s_lshl_b32 s2, s48, 5
	v_readlane_b32 s16, v252, 26
	s_and_b32 s49, s2, 0xfffff800
	v_readlane_b32 s17, v252, 27
	v_add_u32_e32 v0, s49, v155
	s_movk_i32 s2, 0x4a00
	v_mov_b64_e32 v[2:3], s[16:17]
	v_mad_i64_i32 v[2:3], s[16:17], v0, s2, v[2:3]
	s_lshl_b32 s2, s24, 1
	s_load_dwordx2 s[16:17], s[74:75], 0x28
	v_lshl_add_u64 v[2:3], v[2:3], 0, s[2:3]
	v_add_co_u32_e32 v2, vcc, 0x4000, v2
	s_nop 1
	v_addc_co_u32_e32 v3, vcc, 0, v3, vcc
	v_add_co_u32_e32 v244, vcc, 0x4a00, v2
	s_nop 1
	v_addc_co_u32_e32 v245, vcc, 0, v3, vcc
	global_load_ushort v246, v[244:245], off offset:2048
	v_add_co_u32_e32 v244, vcc, 0x4a00, v244
	s_nop 1
	v_addc_co_u32_e32 v245, vcc, 0, v245, vcc
	global_load_ushort v247, v[244:245], off offset:2048
	v_add_co_u32_e32 v244, vcc, 0x4a00, v244
	s_nop 1
	v_addc_co_u32_e32 v245, vcc, 0, v245, vcc
	global_load_ushort v248, v[244:245], off offset:2048
	global_load_ushort v2, v[2:3], off offset:2048
	s_waitcnt vmcnt(0)
	v_lshlrev_b32_e32 v2, 16, v2
	s_waitcnt lgkmcnt(0)
	global_load_dword v3, v4, s[16:17]
	s_waitcnt vmcnt(0)
	v_add_f32_e32 v4, v3, v2
	v_cmp_le_f32_e32 vcc, 0, v4
	s_and_saveexec_b64 s[16:17], vcc
	s_xor_b64 s[16:17], exec, s[16:17]
	s_cbranch_execz .LBB0_1106
	v_mul_f32_e32 v2, 0xbfb8aa3b, v4
	v_rndne_f32_e32 v5, v2
	s_mov_b32 s20, 0xbfb8aa3b
	v_sub_f32_e32 v6, v2, v5
	v_fma_f32 v2, v4, s20, -v2
	v_fmac_f32_e32 v2, 0xb2a5705f, v4
	v_add_f32_e32 v2, v6, v2
	v_cvt_i32_f32_e32 v5, v5
	v_exp_f32_e32 v2, v2
	s_mov_b32 s20, 0x42ce8ed0
	v_cmp_nlt_f32_e32 vcc, s20, v4
	s_mov_b32 s20, 0xc2b17218
	v_ldexp_f32 v2, v2, v5
	v_cndmask_b32_e32 v2, 0, v2, vcc
	v_cmp_ngt_f32_e32 vcc, s20, v4
	s_mov_b32 s20, 0x3f2aaaab
	s_nop 0
	v_cndmask_b32_e32 v2, v202, v2, vcc
	v_add_f32_e32 v6, 1.0, v2
	v_add_f32_e32 v4, -1.0, v6
	v_sub_f32_e32 v5, v4, v6
	v_add_f32_e32 v5, 1.0, v5
	v_sub_f32_e32 v4, v2, v4
	v_add_f32_e32 v7, v4, v5
	v_frexp_mant_f32_e32 v8, v6
	v_cvt_f64_f32_e32 v[4:5], v6
	v_frexp_exp_i32_f64_e32 v4, v[4:5]
	v_cmp_gt_f32_e32 vcc, s20, v8
	s_mov_b32 s20, 0x3f317218
	s_nop 0
	v_subbrev_co_u32_e32 v12, vcc, 0, v4, vcc
	v_sub_u32_e32 v4, 0, v12
	v_ldexp_f32 v5, v6, v4
	v_add_f32_e32 v6, -1.0, v5
	v_add_f32_e32 v8, 1.0, v5
	v_ldexp_f32 v4, v7, v4
	v_add_f32_e32 v7, 1.0, v6
	v_add_f32_e32 v9, -1.0, v8
	v_sub_f32_e32 v7, v5, v7
	v_sub_f32_e32 v5, v5, v9
	v_add_f32_e32 v7, v4, v7
	v_add_f32_e32 v4, v4, v5
	v_add_f32_e32 v13, v8, v4
	v_rcp_f32_e32 v15, v13
	v_sub_f32_e32 v5, v8, v13
	v_add_f32_e32 v14, v4, v5
	v_add_f32_e32 v5, v6, v7
	v_mul_f32_e32 v17, v5, v15
	v_sub_f32_e32 v4, v6, v5
	v_mul_f32_e32 v6, v13, v17
	v_fma_f32 v8, v17, v13, -v6
	v_fmac_f32_e32 v8, v17, v14
	v_add_f32_e32 v16, v7, v4
	v_add_f32_e32 v4, v6, v8
	v_sub_f32_e32 v7, v5, v4
	v_pk_add_f32 v[10:11], v[4:5], v[6:7] neg_lo:[0,1] neg_hi:[0,1]
	v_mov_b32_e32 v9, v4
	v_pk_add_f32 v[4:5], v[10:11], v[8:9] neg_lo:[0,1] neg_hi:[0,1]
	s_nop 0
	v_add_f32_e32 v5, v16, v5
	v_add_f32_e32 v4, v4, v5
	v_add_f32_e32 v5, v7, v4
	v_mul_f32_e32 v16, v15, v5
	v_mul_f32_e32 v6, v13, v16
	v_fma_f32 v8, v16, v13, -v6
	v_fmac_f32_e32 v8, v16, v14
	v_sub_f32_e32 v7, v7, v5
	v_add_f32_e32 v13, v4, v7
	v_add_f32_e32 v4, v6, v8
	v_sub_f32_e32 v7, v5, v4
	v_pk_add_f32 v[10:11], v[4:5], v[6:7] neg_lo:[0,1] neg_hi:[0,1]
	v_mov_b32_e32 v9, v4
	v_pk_add_f32 v[4:5], v[10:11], v[8:9] neg_lo:[0,1] neg_hi:[0,1]
	s_nop 0
	v_add_f32_e32 v5, v13, v5
	v_add_f32_e32 v4, v4, v5
	v_add_f32_e32 v5, v17, v16
	v_add_f32_e32 v4, v7, v4
	v_sub_f32_e32 v6, v5, v17
	v_mul_f32_e32 v4, v15, v4
	v_sub_f32_e32 v6, v16, v6
	v_add_f32_e32 v6, v6, v4
	v_add_f32_e32 v8, v5, v6
	v_mul_f32_e32 v9, v8, v8
	v_mov_b32_e32 v4, 0x3ecc95a3
	v_fmamk_f32 v4, v9, 0x3e9b6dac, v4
	v_fmaak_f32 v179, v9, v4, 0x3f2aaada
	v_cvt_f32_i32_e32 v4, v12
	v_sub_f32_e32 v5, v8, v5
	v_sub_f32_e32 v5, v6, v5
	v_ldexp_f32 v10, v5, 1
	v_mul_f32_e32 v5, v8, v9
	v_ldexp_f32 v7, v8, 1
	v_pk_mul_f32 v[8:9], v[4:5], v[178:179]
	s_nop 0
	v_fma_f32 v6, v4, s20, -v8
	v_fmac_f32_e32 v6, 0xb102e308, v4
	v_pk_add_f32 v[4:5], v[8:9], v[6:7]
	s_mov_b32 s20, 0x7f800000
	v_sub_f32_e32 v7, v5, v7
	v_sub_f32_e32 v7, v9, v7
	v_add_f32_e32 v11, v10, v7
	v_mov_b32_e32 v10, v8
	v_pk_add_f32 v[8:9], v[4:5], v[8:9] neg_lo:[0,1] neg_hi:[0,1]
	v_pk_add_f32 v[12:13], v[4:5], v[10:11]
	v_mov_b32_e32 v7, v4
	v_mov_b32_e32 v9, v13
	v_pk_add_f32 v[14:15], v[6:7], v[8:9] neg_lo:[0,1] neg_hi:[0,1]
	v_pk_add_f32 v[6:7], v[6:7], v[8:9]
	v_mov_b32_e32 v10, v11
	v_pk_add_f32 v[8:9], v[6:7], v[4:5] op_sel:[1,0] op_sel_hi:[0,1] neg_lo:[0,1] neg_hi:[0,1]
	v_pk_add_f32 v[16:17], v[12:13], v[8:9] op_sel_hi:[1,0] neg_lo:[0,1] neg_hi:[0,1]
	v_mov_b32_e32 v12, v13
	v_mov_b32_e32 v13, v7
	v_pk_mov_b32 v[8:9], v[4:5], v[8:9] op_sel:[1,0]
	v_mov_b32_e32 v11, v4
	v_pk_add_f32 v[8:9], v[12:13], v[8:9] neg_lo:[0,1] neg_hi:[0,1]
	v_mov_b32_e32 v16, v14
	v_pk_add_f32 v[4:5], v[10:11], v[8:9] neg_lo:[0,1] neg_hi:[0,1]
	v_mov_b32_e32 v15, v7
	v_pk_add_f32 v[8:9], v[16:17], v[4:5]
	v_cmp_neq_f32_e32 vcc, s20, v2
	v_pk_add_f32 v[10:11], v[8:9], v[8:9] op_sel:[0,1] op_sel_hi:[1,0]
	s_mov_b32 s20, 0x33800000
	v_pk_add_f32 v[6:7], v[6:7], v[10:11] op_sel:[1,0] op_sel_hi:[0,1]
	v_mov_b32_e32 v9, v6
	v_pk_add_f32 v[12:13], v[8:9], v[14:15] neg_lo:[0,1] neg_hi:[0,1]
	v_mov_b32_e32 v5, v10
	v_sub_f32_e32 v7, v8, v12
	v_pk_add_f32 v[4:5], v[4:5], v[12:13] neg_lo:[0,1] neg_hi:[0,1]
	v_sub_f32_e32 v7, v14, v7
	v_add_f32_e32 v4, v4, v7
	v_add_f32_e32 v4, v4, v5
	v_add_f32_e32 v4, v6, v4
	v_cndmask_b32_e32 v4, v202, v4, vcc
	v_cmp_gt_f32_e32 vcc, s20, v2
	s_nop 1
	v_cndmask_b32_e32 v2, v4, v2, vcc
	v_xor_b32_e32 v2, 0x80000000, v2

.LBB0_1108:
	s_or_b64 exec, exec, s[16:17]
	v_readlane_b32 s16, v252, 26
	v_readlane_b32 s17, v252, 27
	v_or_b32_e32 v6, 1, v0
	s_nop 0
	v_mov_b64_e32 v[4:5], s[16:17]
	s_movk_i32 s16, 0x4a00
	v_mad_i64_i32 v[4:5], s[16:17], v6, s16, v[4:5]
	v_lshl_add_u64 v[4:5], v[4:5], 0, s[2:3]
	v_add_co_u32_e32 v4, vcc, 0x4000, v4
	s_nop 1
	v_addc_co_u32_e32 v5, vcc, 0, v5, vcc
	v_mov_b32_e32 v4, v246
	s_waitcnt vmcnt(0)
	v_lshlrev_b32_e32 v4, 16, v4
	v_add_f32_e32 v5, v3, v4
	v_cmp_le_f32_e32 vcc, 0, v5
	s_and_saveexec_b64 s[16:17], vcc
	s_xor_b64 s[16:17], exec, s[16:17]
	s_cbranch_execz .LBB0_1110
	v_mul_f32_e32 v4, 0xbfb8aa3b, v5
	v_rndne_f32_e32 v6, v4
	s_mov_b32 s20, 0xbfb8aa3b
	v_sub_f32_e32 v7, v4, v6
	v_fma_f32 v4, v5, s20, -v4
	v_fmac_f32_e32 v4, 0xb2a5705f, v5
	v_add_f32_e32 v4, v7, v4
	v_cvt_i32_f32_e32 v6, v6
	v_exp_f32_e32 v4, v4
	s_mov_b32 s20, 0x42ce8ed0
	v_cmp_nlt_f32_e32 vcc, s20, v5
	s_mov_b32 s20, 0xc2b17218
	v_ldexp_f32 v4, v4, v6
	v_cndmask_b32_e32 v4, 0, v4, vcc
	v_cmp_ngt_f32_e32 vcc, s20, v5
	s_mov_b32 s20, 0x3f2aaaab
	s_nop 0
	v_cndmask_b32_e32 v18, v202, v4, vcc
	v_add_f32_e32 v6, 1.0, v18
	v_add_f32_e32 v4, -1.0, v6
	v_sub_f32_e32 v5, v4, v6
	v_add_f32_e32 v5, 1.0, v5
	v_sub_f32_e32 v4, v18, v4
	v_add_f32_e32 v7, v4, v5
	v_frexp_mant_f32_e32 v8, v6
	v_cvt_f64_f32_e32 v[4:5], v6
	v_frexp_exp_i32_f64_e32 v4, v[4:5]
	v_cmp_gt_f32_e32 vcc, s20, v8
	s_mov_b32 s20, 0x3f317218
	s_nop 0
	v_subbrev_co_u32_e32 v12, vcc, 0, v4, vcc
	v_sub_u32_e32 v4, 0, v12
	v_ldexp_f32 v5, v6, v4
	v_add_f32_e32 v6, -1.0, v5
	v_add_f32_e32 v8, 1.0, v5
	v_ldexp_f32 v4, v7, v4
	v_add_f32_e32 v7, 1.0, v6
	v_add_f32_e32 v9, -1.0, v8
	v_sub_f32_e32 v7, v5, v7
	v_sub_f32_e32 v5, v5, v9
	v_add_f32_e32 v7, v4, v7
	v_add_f32_e32 v4, v4, v5
	v_add_f32_e32 v13, v8, v4
	v_rcp_f32_e32 v15, v13
	v_sub_f32_e32 v5, v8, v13
	v_add_f32_e32 v14, v4, v5
	v_add_f32_e32 v5, v6, v7
	v_mul_f32_e32 v17, v5, v15
	v_sub_f32_e32 v4, v6, v5
	v_mul_f32_e32 v6, v13, v17
	v_fma_f32 v8, v17, v13, -v6
	v_fmac_f32_e32 v8, v17, v14
	v_add_f32_e32 v16, v7, v4
	v_add_f32_e32 v4, v6, v8
	v_sub_f32_e32 v7, v5, v4
	v_pk_add_f32 v[10:11], v[4:5], v[6:7] neg_lo:[0,1] neg_hi:[0,1]
	v_mov_b32_e32 v9, v4
	v_pk_add_f32 v[4:5], v[10:11], v[8:9] neg_lo:[0,1] neg_hi:[0,1]
	s_nop 0
	v_add_f32_e32 v5, v16, v5
	v_add_f32_e32 v4, v4, v5
	v_add_f32_e32 v5, v7, v4
	v_mul_f32_e32 v16, v15, v5
	v_mul_f32_e32 v6, v13, v16
	v_fma_f32 v8, v16, v13, -v6
	v_fmac_f32_e32 v8, v16, v14
	v_sub_f32_e32 v7, v7, v5
	v_add_f32_e32 v13, v4, v7
	v_add_f32_e32 v4, v6, v8
	v_sub_f32_e32 v7, v5, v4
	v_pk_add_f32 v[10:11], v[4:5], v[6:7] neg_lo:[0,1] neg_hi:[0,1]
	v_mov_b32_e32 v9, v4
	v_pk_add_f32 v[4:5], v[10:11], v[8:9] neg_lo:[0,1] neg_hi:[0,1]
	s_nop 0
	v_add_f32_e32 v5, v13, v5
	v_add_f32_e32 v4, v4, v5
	v_add_f32_e32 v5, v17, v16
	v_add_f32_e32 v4, v7, v4
	v_sub_f32_e32 v6, v5, v17
	v_mul_f32_e32 v4, v15, v4
	v_sub_f32_e32 v6, v16, v6
	v_add_f32_e32 v6, v6, v4
	v_add_f32_e32 v8, v5, v6
	v_mul_f32_e32 v9, v8, v8
	v_mov_b32_e32 v4, 0x3ecc95a3
	v_fmamk_f32 v4, v9, 0x3e9b6dac, v4
	v_fmaak_f32 v179, v9, v4, 0x3f2aaada
	v_cvt_f32_i32_e32 v4, v12
	v_sub_f32_e32 v5, v8, v5
	v_sub_f32_e32 v5, v6, v5
	v_ldexp_f32 v10, v5, 1
	v_mul_f32_e32 v5, v8, v9
	v_ldexp_f32 v7, v8, 1
	v_pk_mul_f32 v[8:9], v[4:5], v[178:179]
	s_nop 0
	v_fma_f32 v6, v4, s20, -v8
	v_fmac_f32_e32 v6, 0xb102e308, v4
	v_pk_add_f32 v[4:5], v[8:9], v[6:7]
	s_mov_b32 s20, 0x7f800000
	v_sub_f32_e32 v7, v5, v7
	v_sub_f32_e32 v7, v9, v7
	v_add_f32_e32 v11, v10, v7
	v_mov_b32_e32 v10, v8
	v_pk_add_f32 v[8:9], v[4:5], v[8:9] neg_lo:[0,1] neg_hi:[0,1]
	v_pk_add_f32 v[12:13], v[4:5], v[10:11]
	v_mov_b32_e32 v7, v4
	v_mov_b32_e32 v9, v13
	v_pk_add_f32 v[14:15], v[6:7], v[8:9] neg_lo:[0,1] neg_hi:[0,1]
	v_pk_add_f32 v[6:7], v[6:7], v[8:9]
	v_mov_b32_e32 v10, v11
	v_pk_add_f32 v[8:9], v[6:7], v[4:5] op_sel:[1,0] op_sel_hi:[0,1] neg_lo:[0,1] neg_hi:[0,1]
	v_pk_add_f32 v[16:17], v[12:13], v[8:9] op_sel_hi:[1,0] neg_lo:[0,1] neg_hi:[0,1]
	v_mov_b32_e32 v12, v13
	v_mov_b32_e32 v13, v7
	v_pk_mov_b32 v[8:9], v[4:5], v[8:9] op_sel:[1,0]
	v_mov_b32_e32 v11, v4
	v_pk_add_f32 v[8:9], v[12:13], v[8:9] neg_lo:[0,1] neg_hi:[0,1]
	v_mov_b32_e32 v16, v14
	v_pk_add_f32 v[4:5], v[10:11], v[8:9] neg_lo:[0,1] neg_hi:[0,1]
	v_mov_b32_e32 v15, v7
	v_pk_add_f32 v[8:9], v[16:17], v[4:5]
	v_cmp_neq_f32_e32 vcc, s20, v18
	v_pk_add_f32 v[10:11], v[8:9], v[8:9] op_sel:[0,1] op_sel_hi:[1,0]
	s_mov_b32 s20, 0x33800000
	v_pk_add_f32 v[6:7], v[6:7], v[10:11] op_sel:[1,0] op_sel_hi:[0,1]
	v_mov_b32_e32 v9, v6
	v_pk_add_f32 v[12:13], v[8:9], v[14:15] neg_lo:[0,1] neg_hi:[0,1]
	v_mov_b32_e32 v5, v10
	v_sub_f32_e32 v7, v8, v12
	v_pk_add_f32 v[4:5], v[4:5], v[12:13] neg_lo:[0,1] neg_hi:[0,1]
	v_sub_f32_e32 v7, v14, v7
	v_add_f32_e32 v4, v4, v7
	v_add_f32_e32 v4, v4, v5
	v_add_f32_e32 v4, v6, v4
	v_cndmask_b32_e32 v4, v202, v4, vcc
	v_cmp_gt_f32_e32 vcc, s20, v18
	s_nop 1
	v_cndmask_b32_e32 v4, v4, v18, vcc
	v_xor_b32_e32 v4, 0x80000000, v4

.LBB0_1112:
	s_or_b64 exec, exec, s[16:17]
	v_readlane_b32 s16, v252, 26
	v_readlane_b32 s17, v252, 27
	v_or_b32_e32 v5, 2, v0
	s_nop 0
	v_mov_b64_e32 v[6:7], s[16:17]
	s_movk_i32 s16, 0x4a00
	v_mad_i64_i32 v[6:7], s[16:17], v5, s16, v[6:7]
	v_lshl_add_u64 v[6:7], v[6:7], 0, s[2:3]
	v_add_co_u32_e32 v6, vcc, 0x4000, v6
	s_nop 1
	v_addc_co_u32_e32 v7, vcc, 0, v7, vcc
	v_mov_b32_e32 v5, v247
	s_waitcnt vmcnt(0)
	v_lshlrev_b32_e32 v5, 16, v5
	v_add_f32_e32 v6, v3, v5
	v_cmp_le_f32_e32 vcc, 0, v6
	s_and_saveexec_b64 s[16:17], vcc
	s_xor_b64 s[16:17], exec, s[16:17]
	s_cbranch_execz .LBB0_1114
	v_mul_f32_e32 v5, 0xbfb8aa3b, v6
	v_rndne_f32_e32 v7, v5
	s_mov_b32 s20, 0xbfb8aa3b
	v_sub_f32_e32 v8, v5, v7
	v_fma_f32 v5, v6, s20, -v5
	v_fmac_f32_e32 v5, 0xb2a5705f, v6
	v_add_f32_e32 v5, v8, v5
	v_cvt_i32_f32_e32 v7, v7
	v_exp_f32_e32 v5, v5
	s_mov_b32 s20, 0x42ce8ed0
	v_cmp_nlt_f32_e32 vcc, s20, v6
	s_mov_b32 s20, 0xc2b17218
	v_ldexp_f32 v5, v5, v7
	v_cndmask_b32_e32 v5, 0, v5, vcc
	v_cmp_ngt_f32_e32 vcc, s20, v6
	s_mov_b32 s20, 0x3f2aaaab
	s_nop 0
	v_cndmask_b32_e32 v5, v202, v5, vcc
	v_add_f32_e32 v8, 1.0, v5
	v_add_f32_e32 v6, -1.0, v8
	v_sub_f32_e32 v7, v6, v8
	v_add_f32_e32 v7, 1.0, v7
	v_sub_f32_e32 v6, v5, v6
	v_add_f32_e32 v9, v6, v7
	v_frexp_mant_f32_e32 v10, v8
	v_cvt_f64_f32_e32 v[6:7], v8
	v_frexp_exp_i32_f64_e32 v6, v[6:7]
	v_cmp_gt_f32_e32 vcc, s20, v10
	s_mov_b32 s20, 0x3f317218
	s_nop 0
	v_subbrev_co_u32_e32 v14, vcc, 0, v6, vcc
	v_sub_u32_e32 v6, 0, v14
	v_ldexp_f32 v7, v8, v6
	v_add_f32_e32 v8, -1.0, v7
	v_add_f32_e32 v10, 1.0, v7
	v_ldexp_f32 v6, v9, v6
	v_add_f32_e32 v9, 1.0, v8
	v_add_f32_e32 v11, -1.0, v10
	v_sub_f32_e32 v9, v7, v9
	v_sub_f32_e32 v7, v7, v11
	v_add_f32_e32 v9, v6, v9
	v_add_f32_e32 v6, v6, v7
	v_add_f32_e32 v15, v10, v6
	v_rcp_f32_e32 v17, v15
	v_sub_f32_e32 v7, v10, v15
	v_add_f32_e32 v16, v6, v7
	v_add_f32_e32 v7, v8, v9
	v_mul_f32_e32 v19, v7, v17
	v_sub_f32_e32 v6, v8, v7
	v_mul_f32_e32 v8, v15, v19
	v_fma_f32 v10, v19, v15, -v8
	v_fmac_f32_e32 v10, v19, v16
	v_add_f32_e32 v18, v9, v6
	v_add_f32_e32 v6, v8, v10
	v_sub_f32_e32 v9, v7, v6
	v_pk_add_f32 v[12:13], v[6:7], v[8:9] neg_lo:[0,1] neg_hi:[0,1]
	v_mov_b32_e32 v11, v6
	v_pk_add_f32 v[6:7], v[12:13], v[10:11] neg_lo:[0,1] neg_hi:[0,1]
	s_nop 0
	v_add_f32_e32 v7, v18, v7
	v_add_f32_e32 v6, v6, v7
	v_add_f32_e32 v7, v9, v6
	v_mul_f32_e32 v18, v17, v7
	v_mul_f32_e32 v8, v15, v18
	v_fma_f32 v10, v18, v15, -v8
	v_fmac_f32_e32 v10, v18, v16
	v_sub_f32_e32 v9, v9, v7
	v_add_f32_e32 v15, v6, v9
	v_add_f32_e32 v6, v8, v10
	v_sub_f32_e32 v9, v7, v6
	v_pk_add_f32 v[12:13], v[6:7], v[8:9] neg_lo:[0,1] neg_hi:[0,1]
	v_mov_b32_e32 v11, v6
	v_pk_add_f32 v[6:7], v[12:13], v[10:11] neg_lo:[0,1] neg_hi:[0,1]
	s_nop 0
	v_add_f32_e32 v7, v15, v7
	v_add_f32_e32 v6, v6, v7
	v_add_f32_e32 v7, v19, v18
	v_add_f32_e32 v6, v9, v6
	v_sub_f32_e32 v8, v7, v19
	v_mul_f32_e32 v6, v17, v6
	v_sub_f32_e32 v8, v18, v8
	v_add_f32_e32 v8, v8, v6
	v_add_f32_e32 v10, v7, v8
	v_mul_f32_e32 v11, v10, v10
	v_mov_b32_e32 v6, 0x3ecc95a3
	v_fmamk_f32 v6, v11, 0x3e9b6dac, v6
	v_fmaak_f32 v179, v11, v6, 0x3f2aaada
	v_cvt_f32_i32_e32 v6, v14
	v_sub_f32_e32 v7, v10, v7
	v_sub_f32_e32 v7, v8, v7
	v_ldexp_f32 v12, v7, 1
	v_mul_f32_e32 v7, v10, v11
	v_ldexp_f32 v9, v10, 1
	v_pk_mul_f32 v[10:11], v[6:7], v[178:179]
	s_nop 0
	v_fma_f32 v8, v6, s20, -v10
	v_fmac_f32_e32 v8, 0xb102e308, v6
	v_pk_add_f32 v[6:7], v[10:11], v[8:9]
	s_mov_b32 s20, 0x7f800000
	v_sub_f32_e32 v9, v7, v9
	v_sub_f32_e32 v9, v11, v9
	v_add_f32_e32 v13, v12, v9
	v_mov_b32_e32 v12, v10
	v_pk_add_f32 v[10:11], v[6:7], v[10:11] neg_lo:[0,1] neg_hi:[0,1]
	v_pk_add_f32 v[14:15], v[6:7], v[12:13]
	v_mov_b32_e32 v9, v6
	v_mov_b32_e32 v11, v15
	v_pk_add_f32 v[16:17], v[8:9], v[10:11] neg_lo:[0,1] neg_hi:[0,1]
	v_pk_add_f32 v[8:9], v[8:9], v[10:11]
	v_mov_b32_e32 v12, v13
	v_pk_add_f32 v[10:11], v[8:9], v[6:7] op_sel:[1,0] op_sel_hi:[0,1] neg_lo:[0,1] neg_hi:[0,1]
	v_pk_add_f32 v[18:19], v[14:15], v[10:11] op_sel_hi:[1,0] neg_lo:[0,1] neg_hi:[0,1]
	v_mov_b32_e32 v14, v15
	v_mov_b32_e32 v15, v9
	v_pk_mov_b32 v[10:11], v[6:7], v[10:11] op_sel:[1,0]
	v_mov_b32_e32 v13, v6
	v_pk_add_f32 v[10:11], v[14:15], v[10:11] neg_lo:[0,1] neg_hi:[0,1]
	v_mov_b32_e32 v18, v16
	v_pk_add_f32 v[6:7], v[12:13], v[10:11] neg_lo:[0,1] neg_hi:[0,1]
	v_mov_b32_e32 v17, v9
	v_pk_add_f32 v[10:11], v[18:19], v[6:7]
	v_cmp_neq_f32_e32 vcc, s20, v5
	v_pk_add_f32 v[12:13], v[10:11], v[10:11] op_sel:[0,1] op_sel_hi:[1,0]
	s_mov_b32 s20, 0x33800000
	v_pk_add_f32 v[8:9], v[8:9], v[12:13] op_sel:[1,0] op_sel_hi:[0,1]
	v_mov_b32_e32 v11, v8
	v_pk_add_f32 v[14:15], v[10:11], v[16:17] neg_lo:[0,1] neg_hi:[0,1]
	v_mov_b32_e32 v7, v12
	v_sub_f32_e32 v9, v10, v14
	v_pk_add_f32 v[6:7], v[6:7], v[14:15] neg_lo:[0,1] neg_hi:[0,1]
	v_sub_f32_e32 v9, v16, v9
	v_add_f32_e32 v6, v6, v9
	v_add_f32_e32 v6, v6, v7
	v_add_f32_e32 v6, v8, v6
	v_cndmask_b32_e32 v6, v202, v6, vcc
	v_cmp_gt_f32_e32 vcc, s20, v5
	s_nop 1
	v_cndmask_b32_e32 v5, v6, v5, vcc
	v_xor_b32_e32 v5, 0x80000000, v5

.LBB0_1116:
	s_or_b64 exec, exec, s[16:17]
	v_readlane_b32 s16, v252, 26
	v_readlane_b32 s17, v252, 27
	v_or_b32_e32 v0, 3, v0
	s_nop 0
	v_mov_b64_e32 v[6:7], s[16:17]
	s_movk_i32 s16, 0x4a00
	v_mad_i64_i32 v[6:7], s[16:17], v0, s16, v[6:7]
	v_lshl_add_u64 v[6:7], v[6:7], 0, s[2:3]
	v_add_co_u32_e32 v6, vcc, 0x4000, v6
	s_nop 1
	v_addc_co_u32_e32 v7, vcc, 0, v7, vcc
	v_mov_b32_e32 v0, v248
	s_waitcnt vmcnt(0)
	v_lshlrev_b32_e32 v0, 16, v0
	v_add_f32_e32 v0, v3, v0
	v_cmp_le_f32_e32 vcc, 0, v0
	s_and_saveexec_b64 s[16:17], vcc
	s_xor_b64 s[16:17], exec, s[16:17]
	s_cbranch_execz .LBB0_1118
	v_mul_f32_e32 v3, 0xbfb8aa3b, v0
	v_rndne_f32_e32 v6, v3
	s_mov_b32 s2, 0xbfb8aa3b
	v_sub_f32_e32 v7, v3, v6
	v_fma_f32 v3, v0, s2, -v3
	v_fmac_f32_e32 v3, 0xb2a5705f, v0
	v_add_f32_e32 v3, v7, v3
	v_cvt_i32_f32_e32 v6, v6
	v_exp_f32_e32 v3, v3
	s_mov_b32 s2, 0x42ce8ed0
	v_cmp_nlt_f32_e32 vcc, s2, v0
	s_mov_b32 s2, 0xc2b17218
	v_ldexp_f32 v3, v3, v6
	v_cndmask_b32_e32 v3, 0, v3, vcc
	v_cmp_ngt_f32_e32 vcc, s2, v0
	s_mov_b32 s2, 0x3f2aaaab
	s_nop 0
	v_cndmask_b32_e32 v0, v202, v3, vcc
	v_add_f32_e32 v3, 1.0, v0
	v_add_f32_e32 v6, -1.0, v3
	v_sub_f32_e32 v7, v6, v3
	v_add_f32_e32 v7, 1.0, v7
	v_sub_f32_e32 v6, v0, v6
	v_add_f32_e32 v8, v6, v7
	v_frexp_mant_f32_e32 v9, v3
	v_cvt_f64_f32_e32 v[6:7], v3
	v_frexp_exp_i32_f64_e32 v6, v[6:7]
	v_cmp_gt_f32_e32 vcc, s2, v9
	s_mov_b32 s2, 0x3f317218
	s_nop 0
	v_subbrev_co_u32_e32 v14, vcc, 0, v6, vcc
	v_sub_u32_e32 v6, 0, v14
	v_ldexp_f32 v3, v3, v6
	v_ldexp_f32 v6, v8, v6
	v_add_f32_e32 v8, -1.0, v3
	v_add_f32_e32 v7, 1.0, v8
	v_sub_f32_e32 v7, v3, v7
	v_add_f32_e32 v9, v6, v7
	v_add_f32_e32 v7, 1.0, v3
	v_add_f32_e32 v10, -1.0, v7
	v_sub_f32_e32 v3, v3, v10
	v_add_f32_e32 v3, v6, v3
	v_add_f32_e32 v15, v7, v3
	v_rcp_f32_e32 v16, v15
	v_sub_f32_e32 v6, v7, v15
	v_add_f32_e32 v7, v8, v9
	v_add_f32_e32 v3, v3, v6
	v_mul_f32_e32 v18, v7, v16
	v_sub_f32_e32 v6, v8, v7
	v_mul_f32_e32 v8, v15, v18
	v_fma_f32 v10, v18, v15, -v8
	v_fmac_f32_e32 v10, v18, v3
	v_add_f32_e32 v17, v9, v6
	v_add_f32_e32 v6, v8, v10
	v_sub_f32_e32 v9, v7, v6
	v_pk_add_f32 v[12:13], v[6:7], v[8:9] neg_lo:[0,1] neg_hi:[0,1]
	v_mov_b32_e32 v11, v6
	v_pk_add_f32 v[6:7], v[12:13], v[10:11] neg_lo:[0,1] neg_hi:[0,1]
	s_nop 0
	v_add_f32_e32 v7, v17, v7
	v_add_f32_e32 v6, v6, v7
	v_add_f32_e32 v7, v9, v6
	v_mul_f32_e32 v17, v16, v7
	v_mul_f32_e32 v8, v15, v17
	v_fma_f32 v10, v17, v15, -v8
	v_fmac_f32_e32 v10, v17, v3
	v_sub_f32_e32 v3, v9, v7
	v_add_f32_e32 v3, v6, v3
	v_add_f32_e32 v6, v8, v10
	v_sub_f32_e32 v9, v7, v6
	v_pk_add_f32 v[12:13], v[6:7], v[8:9] neg_lo:[0,1] neg_hi:[0,1]
	v_mov_b32_e32 v11, v6
	v_pk_add_f32 v[6:7], v[12:13], v[10:11] neg_lo:[0,1] neg_hi:[0,1]
	s_nop 0
	v_add_f32_e32 v3, v3, v7
	v_add_f32_e32 v3, v6, v3
	v_add_f32_e32 v7, v18, v17
	v_add_f32_e32 v3, v9, v3
	v_sub_f32_e32 v6, v7, v18
	v_mul_f32_e32 v3, v16, v3
	v_sub_f32_e32 v6, v17, v6
	v_add_f32_e32 v3, v6, v3
	v_add_f32_e32 v8, v7, v3
	v_mul_f32_e32 v10, v8, v8
	v_mov_b32_e32 v6, 0x3ecc95a3
	v_fmamk_f32 v6, v10, 0x3e9b6dac, v6
	v_fmaak_f32 v179, v10, v6, 0x3f2aaada
	v_cvt_f32_i32_e32 v6, v14
	v_sub_f32_e32 v7, v8, v7
	v_sub_f32_e32 v3, v3, v7
	v_mul_f32_e32 v7, v8, v10
	v_pk_mul_f32 v[10:11], v[6:7], v[178:179]
	v_ldexp_f32 v9, v8, 1
	v_fma_f32 v8, v6, s2, -v10
	v_fmac_f32_e32 v8, 0xb102e308, v6
	v_pk_add_f32 v[6:7], v[10:11], v[8:9]
	v_ldexp_f32 v3, v3, 1
	v_sub_f32_e32 v9, v7, v9
	v_sub_f32_e32 v9, v11, v9
	v_add_f32_e32 v13, v3, v9
	v_mov_b32_e32 v12, v10
	v_pk_add_f32 v[10:11], v[6:7], v[10:11] neg_lo:[0,1] neg_hi:[0,1]
	v_pk_add_f32 v[14:15], v[6:7], v[12:13]
	v_mov_b32_e32 v9, v6
	v_mov_b32_e32 v11, v15
	v_pk_add_f32 v[16:17], v[8:9], v[10:11] neg_lo:[0,1] neg_hi:[0,1]
	v_pk_add_f32 v[8:9], v[8:9], v[10:11]
	v_mov_b32_e32 v12, v13
	v_pk_add_f32 v[10:11], v[8:9], v[6:7] op_sel:[1,0] op_sel_hi:[0,1] neg_lo:[0,1] neg_hi:[0,1]
	v_pk_add_f32 v[18:19], v[14:15], v[10:11] op_sel_hi:[1,0] neg_lo:[0,1] neg_hi:[0,1]
	v_mov_b32_e32 v14, v15
	v_mov_b32_e32 v15, v9
	v_pk_mov_b32 v[10:11], v[6:7], v[10:11] op_sel:[1,0]
	v_mov_b32_e32 v13, v6
	v_pk_add_f32 v[10:11], v[14:15], v[10:11] neg_lo:[0,1] neg_hi:[0,1]
	v_mov_b32_e32 v18, v16
	v_pk_add_f32 v[6:7], v[12:13], v[10:11] neg_lo:[0,1] neg_hi:[0,1]
	v_mov_b32_e32 v17, v9
	v_pk_add_f32 v[10:11], v[18:19], v[6:7]
	s_mov_b32 s2, 0x7f800000
	v_pk_add_f32 v[12:13], v[10:11], v[10:11] op_sel:[0,1] op_sel_hi:[1,0]
	v_cmp_neq_f32_e32 vcc, s2, v0
	v_pk_add_f32 v[8:9], v[8:9], v[12:13] op_sel:[1,0] op_sel_hi:[0,1]
	v_mov_b32_e32 v11, v8
	v_pk_add_f32 v[14:15], v[10:11], v[16:17] neg_lo:[0,1] neg_hi:[0,1]
	v_mov_b32_e32 v7, v12
	v_sub_f32_e32 v3, v10, v14
	v_pk_add_f32 v[6:7], v[6:7], v[14:15] neg_lo:[0,1] neg_hi:[0,1]
	v_sub_f32_e32 v3, v16, v3
	v_add_f32_e32 v3, v6, v3
	v_add_f32_e32 v3, v3, v7
	v_add_f32_e32 v3, v8, v3
	s_mov_b32 s2, 0x33800000
	v_cndmask_b32_e32 v3, v202, v3, vcc
	v_cmp_gt_f32_e32 vcc, s2, v0
	s_nop 1
	v_cndmask_b32_e32 v0, v3, v0, vcc
	v_xor_b32_e32 v6, 0x80000000, v0

.LBB0_1164:
	s_ashr_i32 s0, s16, 5
	s_lshl_b32 s2, s16, 8
	s_lshl_b32 s1, s0, 11
	s_and_b32 s2, s2, 0x700
	s_or_b32 s28, s1, s2
	v_add_u32_e32 v0, s28, v152
	s_lshl_b32 s1, s16, 4
	v_mad_i64_i32 v[2:3], s[6:7], v0, s17, 0
	s_and_b32 s29, s1, 0x180
	v_lshl_add_u64 v[2:3], v[2:3], 1, s[4:5]
	s_lshl_b32 s2, s29, 1
	v_lshl_add_u64 v[2:3], v[2:3], 0, s[2:3]
	v_mov_b32_e32 v149, v1
	s_waitcnt vmcnt(0)
	v_lshl_add_u64 v[30:31], v[2:3], 0, v[148:149]
	global_load_dwordx4 v[2:5], v[30:31], off
	global_load_dwordx4 v[6:9], v[30:31], off offset:32
	global_load_dwordx4 v[10:13], v[30:31], off offset:64
	global_load_dwordx4 v[14:17], v[30:31], off offset:96
	global_load_dwordx4 v[18:21], v[30:31], off offset:128
	global_load_dwordx4 v[22:25], v[30:31], off offset:160
	global_load_dwordx4 v[26:29], v[30:31], off offset:192
	s_nop 0
	global_load_dwordx4 v[30:33], v[30:31], off offset:224
	s_lshl_b32 s0, s0, 8
	s_ashr_i32 s1, s0, 31
	s_lshl_b64 s[0:1], s[0:1], 13
	s_add_u32 s0, s20, s0
	s_addc_u32 s1, s21, s1
	s_add_u32 s6, s0, s2
	s_addc_u32 s7, s1, 0
	v_mov_b32_e32 v151, v1
	s_mov_b64 s[10:11], 0x400
	s_mov_b64 s[14:15], 0x480
	s_mov_b32 s31, 0
	v_mov_b32_e32 v155, 0
	v_mov_b32_e32 v158, 0xf149f2ca
	s_mov_b32 s34, 0
	s_mov_b32 s35, 0
	s_mov_b32 s36, 0
	s_waitcnt vmcnt(7)
	v_lshlrev_b32_e32 v0, 16, v2
	v_and_b32_e32 v2, 0xffff0000, v2
	v_lshlrev_b32_e32 v34, 16, v3
	v_and_b32_e32 v3, 0xffff0000, v3
	v_lshlrev_b32_e32 v35, 16, v4
	v_and_b32_e32 v4, 0xffff0000, v4
	s_waitcnt vmcnt(6)
	v_lshlrev_b32_e32 v39, 16, v8
	v_and_b32_e32 v8, 0xffff0000, v8
	v_mul_f32_e32 v0, 0x3e0293ee, v0
	v_mul_f32_e32 v2, 0x3e0293ee, v2
	v_mul_f32_e32 v3, 0x3e0293ee, v3
	v_mul_f32_e32 v4, 0x3e0293ee, v4
	v_lshlrev_b32_e32 v36, 16, v5
	v_and_b32_e32 v5, 0xffff0000, v5
	v_lshlrev_b32_e32 v37, 16, v6
	v_and_b32_e32 v6, 0xffff0000, v6
	v_lshlrev_b32_e32 v38, 16, v7
	v_and_b32_e32 v7, 0xffff0000, v7
	v_mul_f32_e32 v34, 0x3e0293ee, v34
	v_mul_f32_e32 v35, 0x3e0293ee, v35
	v_mul_f32_e32 v8, 0x3e0293ee, v8
	v_cvt_pk_bf16_f32 v112, v0, v2
	v_cvt_pk_bf16_f32 v113, v34, v3
	v_cvt_pk_bf16_f32 v114, v35, v4
	s_waitcnt vmcnt(4)
	v_lshlrev_b32_e32 v0, 16, v16
	v_and_b32_e32 v2, 0xffff0000, v16
	v_lshlrev_b32_e32 v3, 16, v17
	v_and_b32_e32 v4, 0xffff0000, v17
	v_lshlrev_b32_e32 v40, 16, v9
	v_and_b32_e32 v9, 0xffff0000, v9
	v_lshlrev_b32_e32 v41, 16, v10
	v_and_b32_e32 v10, 0xffff0000, v10
	v_lshlrev_b32_e32 v42, 16, v11
	v_and_b32_e32 v11, 0xffff0000, v11
	v_lshlrev_b32_e32 v43, 16, v12
	v_and_b32_e32 v12, 0xffff0000, v12
	v_lshlrev_b32_e32 v44, 16, v13
	v_and_b32_e32 v13, 0xffff0000, v13
	v_lshlrev_b32_e32 v45, 16, v14
	v_and_b32_e32 v14, 0xffff0000, v14
	v_lshlrev_b32_e32 v46, 16, v15
	v_and_b32_e32 v15, 0xffff0000, v15
	v_mul_f32_e32 v36, 0x3e0293ee, v36
	v_mul_f32_e32 v5, 0x3e0293ee, v5
	v_mul_f32_e32 v37, 0x3e0293ee, v37
	v_mul_f32_e32 v6, 0x3e0293ee, v6
	v_mul_f32_e32 v38, 0x3e0293ee, v38
	v_mul_f32_e32 v7, 0x3e0293ee, v7
	v_mul_f32_e32 v39, 0x3e0293ee, v39
	v_cvt_pk_bf16_f32 v115, v36, v5
	v_cvt_pk_bf16_f32 v116, v37, v6
	v_cvt_pk_bf16_f32 v117, v38, v7
	v_cvt_pk_bf16_f32 v118, v39, v8
	v_mul_f32_e32 v0, 0x3e0293ee, v0
	v_mul_f32_e32 v2, 0x3e0293ee, v2
	v_mul_f32_e32 v3, 0x3e0293ee, v3
	v_mul_f32_e32 v4, 0x3e0293ee, v4
	s_waitcnt vmcnt(3)
	v_and_b32_e32 v8, 0xffff0000, v21
	v_mul_f32_e32 v40, 0x3e0293ee, v40
	v_mul_f32_e32 v9, 0x3e0293ee, v9
	v_mul_f32_e32 v41, 0x3e0293ee, v41
	v_mul_f32_e32 v10, 0x3e0293ee, v10
	v_mul_f32_e32 v42, 0x3e0293ee, v42
	v_mul_f32_e32 v11, 0x3e0293ee, v11
	v_mul_f32_e32 v43, 0x3e0293ee, v43
	v_mul_f32_e32 v12, 0x3e0293ee, v12
	v_mul_f32_e32 v44, 0x3e0293ee, v44
	v_mul_f32_e32 v13, 0x3e0293ee, v13
	v_mul_f32_e32 v45, 0x3e0293ee, v45
	v_mul_f32_e32 v14, 0x3e0293ee, v14
	v_mul_f32_e32 v46, 0x3e0293ee, v46
	v_mul_f32_e32 v15, 0x3e0293ee, v15
	v_cvt_pk_bf16_f32 v119, v40, v9
	v_cvt_pk_bf16_f32 v120, v41, v10
	v_cvt_pk_bf16_f32 v121, v42, v11
	v_cvt_pk_bf16_f32 v122, v43, v12
	v_cvt_pk_bf16_f32 v123, v44, v13
	v_cvt_pk_bf16_f32 v124, v45, v14
	v_cvt_pk_bf16_f32 v125, v46, v15
	v_cvt_pk_bf16_f32 v126, v0, v2
	v_cvt_pk_bf16_f32 v127, v3, v4
	v_lshlrev_b32_e32 v0, 16, v18
	v_and_b32_e32 v2, 0xffff0000, v18
	v_lshlrev_b32_e32 v3, 16, v19
	v_and_b32_e32 v4, 0xffff0000, v19
	v_lshlrev_b32_e32 v5, 16, v20
	v_and_b32_e32 v6, 0xffff0000, v20
	v_lshlrev_b32_e32 v7, 16, v21
	v_mul_f32_e32 v8, 0x3e0293ee, v8
	v_mul_f32_e32 v0, 0x3e0293ee, v0
	v_mul_f32_e32 v2, 0x3e0293ee, v2
	v_mul_f32_e32 v3, 0x3e0293ee, v3
	v_mul_f32_e32 v4, 0x3e0293ee, v4
	v_mul_f32_e32 v5, 0x3e0293ee, v5
	v_mul_f32_e32 v6, 0x3e0293ee, v6
	v_mul_f32_e32 v7, 0x3e0293ee, v7
	v_cvt_pk_bf16_f32 v128, v0, v2
	v_cvt_pk_bf16_f32 v129, v3, v4
	v_cvt_pk_bf16_f32 v130, v5, v6
	v_cvt_pk_bf16_f32 v131, v7, v8
	s_waitcnt vmcnt(2)
	v_and_b32_e32 v8, 0xffff0000, v25
	v_lshlrev_b32_e32 v0, 16, v22
	v_and_b32_e32 v2, 0xffff0000, v22
	v_lshlrev_b32_e32 v3, 16, v23
	v_and_b32_e32 v4, 0xffff0000, v23
	v_lshlrev_b32_e32 v5, 16, v24
	v_and_b32_e32 v6, 0xffff0000, v24
	v_lshlrev_b32_e32 v7, 16, v25
	v_mul_f32_e32 v8, 0x3e0293ee, v8
	v_mul_f32_e32 v0, 0x3e0293ee, v0
	v_mul_f32_e32 v2, 0x3e0293ee, v2
	v_mul_f32_e32 v3, 0x3e0293ee, v3
	v_mul_f32_e32 v4, 0x3e0293ee, v4
	v_mul_f32_e32 v5, 0x3e0293ee, v5
	v_mul_f32_e32 v6, 0x3e0293ee, v6
	v_mul_f32_e32 v7, 0x3e0293ee, v7
	v_cvt_pk_bf16_f32 v132, v0, v2
	v_cvt_pk_bf16_f32 v133, v3, v4
	v_cvt_pk_bf16_f32 v134, v5, v6
	v_cvt_pk_bf16_f32 v135, v7, v8
	s_waitcnt vmcnt(1)
	v_and_b32_e32 v8, 0xffff0000, v29
	v_lshlrev_b32_e32 v0, 16, v26
	v_and_b32_e32 v2, 0xffff0000, v26
	v_lshlrev_b32_e32 v3, 16, v27
	v_and_b32_e32 v4, 0xffff0000, v27
	v_lshlrev_b32_e32 v5, 16, v28
	v_and_b32_e32 v6, 0xffff0000, v28
	v_lshlrev_b32_e32 v7, 16, v29
	v_mul_f32_e32 v8, 0x3e0293ee, v8
	v_mul_f32_e32 v0, 0x3e0293ee, v0
	v_mul_f32_e32 v2, 0x3e0293ee, v2
	v_mul_f32_e32 v3, 0x3e0293ee, v3
	v_mul_f32_e32 v4, 0x3e0293ee, v4
	v_mul_f32_e32 v5, 0x3e0293ee, v5
	v_mul_f32_e32 v6, 0x3e0293ee, v6
	v_mul_f32_e32 v7, 0x3e0293ee, v7
	v_cvt_pk_bf16_f32 v136, v0, v2
	v_cvt_pk_bf16_f32 v137, v3, v4
	v_cvt_pk_bf16_f32 v138, v5, v6
	v_cvt_pk_bf16_f32 v139, v7, v8
	s_waitcnt vmcnt(0)
	v_and_b32_e32 v8, 0xffff0000, v33
	v_lshlrev_b32_e32 v0, 16, v30
	v_and_b32_e32 v2, 0xffff0000, v30
	v_lshlrev_b32_e32 v3, 16, v31
	v_and_b32_e32 v4, 0xffff0000, v31
	v_lshlrev_b32_e32 v5, 16, v32
	v_and_b32_e32 v6, 0xffff0000, v32
	v_lshlrev_b32_e32 v7, 16, v33
	v_mul_f32_e32 v8, 0x3e0293ee, v8
	v_mul_f32_e32 v0, 0x3e0293ee, v0
	v_mul_f32_e32 v2, 0x3e0293ee, v2
	v_mul_f32_e32 v3, 0x3e0293ee, v3
	v_mul_f32_e32 v4, 0x3e0293ee, v4
	v_mul_f32_e32 v5, 0x3e0293ee, v5
	v_mul_f32_e32 v6, 0x3e0293ee, v6
	v_mul_f32_e32 v7, 0x3e0293ee, v7
	v_cvt_pk_bf16_f32 v140, v0, v2
	v_cvt_pk_bf16_f32 v141, v3, v4
	v_cvt_pk_bf16_f32 v142, v5, v6
	v_cvt_pk_bf16_f32 v143, v7, v8
	v_mov_b32_e32 v8, v198
	v_mov_b32_e32 v14, v1
	v_readfirstlane_b32 s0, v8
	s_ashr_i32 s12, s0, 6
	v_lshrrev_b32_e32 v9, 1, v8
	s_lshl_b32 s0, s12, 3
	v_bfe_u32 v10, v8, 4, 2
	v_bfe_u32 v0, v8, 2, 3
	s_lshl_b32 s1, s12, 2
	v_lshlrev_b32_e32 v4, 3, v8
	v_bitop3_b32 v0, s0, v204, v0 bitop3:0xc8
	v_and_b32_e32 v3, 8, v9
	s_and_b32 s1, s1, 4
	v_and_b32_e32 v6, 24, v4
	v_bitop3_b32 v4, v10, v8, 15 bitop3:0x78
	v_and_b32_e32 v2, 15, v8
	v_or3_b32 v0, v3, v0, s1
	v_lshlrev_b32_e32 v11, 3, v4
	v_or_b32_e32 v4, 4, v10
	v_lshlrev_b32_e32 v7, 12, v0
	v_or_b32_e32 v0, s0, v10
	v_or_b32_e32 v4, s0, v4
	v_bitop3_b32 v2, v10, v2, 4 bitop3:0x36
	s_lshl_b32 s0, s12, 11
	s_add_i32 s1, 0, 0x10000
	v_and_b32_e32 v3, 32, v8
	v_lshl_or_b32 v0, v0, 12, v11
	v_lshlrev_b32_e32 v12, 3, v2
	s_add_i32 s2, s1, s0
	v_lshl_or_b32 v2, v4, 12, v12
	v_lshl_add_u64 v[4:5], v[0:1], 1, s[6:7]
	s_mov_b32 m0, s2
	v_or3_b32 v150, v3, v6, v7
	global_load_lds_dwordx4 v[4:5], off
	v_lshl_add_u64 v[4:5], v[150:151], 1, s[6:7]
	s_add_i32 s30, s0, 0
	v_lshl_add_u64 v[6:7], v[4:5], 0, s[10:11]
	s_mov_b32 m0, s30
	v_mov_b32_e32 v3, v1
	s_or_b32 s8, s0, 0x400
	global_load_lds_dwordx4 v[6:7], off
	v_lshl_add_u64 v[6:7], v[2:3], 1, s[6:7]
	s_add_i32 m0, s1, s8
	v_lshl_add_u64 v[4:5], v[4:5], 0, s[14:15]
	global_load_lds_dwordx4 v[6:7], off
	s_add_i32 m0, s30, 0x400
	v_add_u32_e32 v0, 0x40000, v0
	s_add_i32 s1, 0, 0x14000
	global_load_lds_dwordx4 v[4:5], off
	v_lshl_add_u64 v[4:5], v[0:1], 1, s[6:7]
	s_add_i32 m0, s1, s0
	v_add_u32_e32 v0, 0x40000, v150
	global_load_lds_dwordx4 v[4:5], off
	v_lshl_add_u64 v[4:5], v[0:1], 1, s[6:7]
	v_lshl_add_u64 v[4:5], v[4:5], 0, s[10:11]
	s_add_i32 m0, s30, 0x4000
	v_add_u32_e32 v0, 0x40000, v2
	global_load_lds_dwordx4 v[4:5], off
	v_lshl_add_u64 v[2:3], v[0:1], 1, s[6:7]
	s_add_i32 m0, s1, s8
	v_add_u32_e32 v0, 0x40040, v150
	global_load_lds_dwordx4 v[2:3], off
	v_lshl_add_u64 v[2:3], v[0:1], 1, s[6:7]
	v_lshl_add_u64 v[2:3], v[2:3], 0, s[10:11]
	s_add_i32 m0, s30, 0x4400
	v_and_b32_e32 v0, 63, v8
	global_load_lds_dwordx4 v[2:3], off
	v_and_b32_e32 v3, 0x3fffffc0, v8
	v_readlane_b32 s0, v254, 1
	v_lshlrev_b32_e32 v4, 4, v8
	v_and_b32_e32 v5, 0xc0, v4
	v_lshl_add_u32 v151, v3, 2, s0
	v_lshlrev_b32_e32 v3, 3, v0
	v_lshlrev_b32_e32 v6, 1, v8
	s_cmp_gt_i32 s12, 3
	v_and_or_b32 v5, v3, 24, v5
	v_and_b32_e32 v6, 32, v6
	v_and_b32_e32 v3, 0x100, v3
	s_cselect_b64 s[8:9], -1, 0
	s_cmp_lt_i32 s12, 4
	v_or3_b32 v149, v5, v6, v3
	v_and_b32_e32 v153, 16, v9
	v_and_b32_e32 v3, 0x70, v4
	s_movk_i32 s0, 0x60
	s_cselect_b64 s[10:11], -1, 0
	s_lshl_b32 s12, s12, 15
	v_and_b32_e32 v2, 31, v8
	v_bitop3_b32 v161, v153, v3, s0 bitop3:0x36
	s_waitcnt vmcnt(4)
	v_cmp_gt_u32_e64 s[0:1], 32, v0
	s_add_i32 s13, s12, 0x84000
	v_lshlrev_b32_e32 v0, 12, v10
	s_add_i32 s12, s12, 0x80000
	v_mov_b32_e32 v15, v1
	v_lshlrev_b32_e32 v156, 8, v2
	v_bitop3_b32 v157, v9, v3, 16 bitop3:0x6c
	v_bitop3_b32 v159, v153, v3, 32 bitop3:0x36
	v_bitop3_b32 v160, v153, v3, 64 bitop3:0x36
	v_lshl_add_u32 v154, v2, 2, v151
	v_or3_b32 v163, s13, v0, v12
	v_or3_b32 v164, s12, v0, v11
	v_mov_b32_e32 v0, v1
	v_mov_b32_e32 v2, v1
	v_mov_b32_e32 v3, v1
	v_mov_b32_e32 v4, v1
	v_mov_b32_e32 v5, v1
	v_mov_b32_e32 v6, v1
	v_mov_b32_e32 v7, v1
	v_mov_b32_e32 v8, v1
	v_mov_b32_e32 v9, v1
	v_mov_b32_e32 v10, v1
	v_mov_b32_e32 v11, v1
	v_mov_b32_e32 v12, v1
	v_mov_b32_e32 v13, v1
	v_mov_b64_e32 v[30:31], v[14:15]
	v_mov_b64_e32 v[46:47], v[14:15]
	v_mov_b64_e32 v[62:63], v[14:15]
	v_mov_b64_e32 v[78:79], v[14:15]
	v_mov_b64_e32 v[110:111], v[14:15]
	v_mov_b64_e32 v[94:95], v[14:15]
	v_add_u32_e32 v162, 0, v149
	s_mov_b64 s[14:15], 0
	v_mov_b64_e32 v[28:29], v[12:13]
	v_mov_b64_e32 v[26:27], v[10:11]
	v_mov_b64_e32 v[24:25], v[8:9]
	v_mov_b64_e32 v[22:23], v[6:7]
	v_mov_b64_e32 v[20:21], v[4:5]
	v_mov_b64_e32 v[18:19], v[2:3]
	v_mov_b64_e32 v[16:17], v[0:1]
	v_mov_b64_e32 v[44:45], v[12:13]
	v_mov_b64_e32 v[42:43], v[10:11]
	v_mov_b64_e32 v[40:41], v[8:9]
	v_mov_b64_e32 v[38:39], v[6:7]
	v_mov_b64_e32 v[36:37], v[4:5]
	v_mov_b64_e32 v[34:35], v[2:3]
	v_mov_b64_e32 v[32:33], v[0:1]
	v_mov_b64_e32 v[60:61], v[12:13]
	v_mov_b64_e32 v[58:59], v[10:11]
	v_mov_b64_e32 v[56:57], v[8:9]
	v_mov_b64_e32 v[54:55], v[6:7]
	v_mov_b64_e32 v[52:53], v[4:5]
	v_mov_b64_e32 v[50:51], v[2:3]
	v_mov_b64_e32 v[48:49], v[0:1]
	v_mov_b64_e32 v[76:77], v[12:13]
	v_mov_b64_e32 v[74:75], v[10:11]
	v_mov_b64_e32 v[72:73], v[8:9]
	v_mov_b64_e32 v[70:71], v[6:7]
	v_mov_b64_e32 v[68:69], v[4:5]
	v_mov_b64_e32 v[66:67], v[2:3]
	v_mov_b64_e32 v[64:65], v[0:1]
	v_mov_b64_e32 v[108:109], v[12:13]
	v_mov_b64_e32 v[106:107], v[10:11]
	v_mov_b64_e32 v[104:105], v[8:9]
	v_mov_b64_e32 v[102:103], v[6:7]
	v_mov_b64_e32 v[100:101], v[4:5]
	v_mov_b64_e32 v[98:99], v[2:3]
	v_mov_b64_e32 v[96:97], v[0:1]
	v_mov_b64_e32 v[92:93], v[12:13]
	v_mov_b64_e32 v[90:91], v[10:11]
	v_mov_b64_e32 v[88:89], v[8:9]
	v_mov_b64_e32 v[86:87], v[6:7]
	v_mov_b64_e32 v[84:85], v[4:5]
	v_mov_b64_e32 v[82:83], v[2:3]
	v_mov_b64_e32 v[80:81], v[0:1]
	s_waitcnt vmcnt(4) lgkmcnt(0)
	s_barrier
	s_cmp_gt_u32 s36, 1
	s_cselect_b64 s[12:13], -1, 0
	s_and_b64 vcc, exec, s[12:13]
	s_cbranch_vccnz .LBB0_1166

.LBB0_1180:
	s_add_i32 s12, s34, 1
	s_cmp_lg_u32 s34, 2
	s_cselect_b32 s34, s12, 0
	s_add_i32 s12, s35, 1
	s_and_b32 s35, s12, 3
	s_add_i32 s36, s36, 1
	s_add_i32 s31, s31, 0x40000
	s_cmp_eq_u32 s31, 0x100000
	s_waitcnt vmcnt(4)
	s_barrier
	s_cbranch_scc1 .LBB0_1184
	s_mov_b64 s[14:15], s[8:9]
	s_cmp_gt_u32 s36, 1
	s_cselect_b64 s[12:13], -1, 0
	s_and_b64 vcc, exec, s[12:13]
	s_cbranch_vccz .LBB0_1165
	s_branch .LBB0_1166

.LBB0_1348:
	s_add_i32 s40, s14, 2
	s_add_u32 s16, s12, 0x80
	s_addc_u32 s15, s13, 0
	s_add_i32 s41, 0, 0x10000
	v_add_u32_e32 v126, s41, v216
	ds_read_b128 v[114:117], v126
	ds_read_b128 v[118:121], v126 offset:1024
	ds_read_b128 v[122:125], v126 offset:2048
	ds_read_b128 v[126:129], v126 offset:3072
	s_cmp_eq_u32 s30, s14
	s_cselect_b32 s14, s4, s16
	s_cselect_b32 s15, s5, s15
	s_cselect_b32 s17, s7, s39
	s_cselect_b32 s16, s6, s38
	v_lshl_add_u64 v[186:187], s[12:13], 0, v[182:183]
	s_add_i32 m0, s23, 0xc000
	ds_read_b128 v[130:133], v218
	ds_read_b128 v[134:137], v218 offset:1024
	ds_read_b128 v[138:141], v218 offset:2048
	ds_read_b128 v[142:145], v218 offset:3072
	ds_read_b128 v[154:157], v218 offset:4096
	ds_read_b128 v[162:165], v218 offset:5120
	ds_read_b128 v[170:173], v218 offset:6144
	ds_read_b128 v[174:177], v218 offset:7168
	global_load_lds_dwordx4 v[186:187], off
	v_lshl_add_u64 v[186:187], s[12:13], 0, v[184:185]
	s_add_i32 m0, s23, 0xe000
	s_nop 0
	global_load_lds_dwordx4 v[186:187], off
	s_waitcnt lgkmcnt(8)
	s_barrier
	s_waitcnt lgkmcnt(0)
	s_setprio 1
	s_waitcnt lgkmcnt(0)
	v_mfma_f32_16x16x32_bf16 v[166:169], v[114:117], v[130:133], v[166:169]
	v_mfma_f32_16x16x32_bf16 v[158:161], v[122:125], v[130:133], v[158:161]
	v_mfma_f32_16x16x32_bf16 v[110:113], v[114:117], v[138:141], v[110:113]
	v_mfma_f32_16x16x32_bf16 v[106:109], v[122:125], v[138:141], v[106:109]
	v_mfma_f32_16x16x32_bf16 v[94:97], v[114:117], v[154:157], v[94:97]
	v_mfma_f32_16x16x32_bf16 v[90:93], v[122:125], v[154:157], v[90:93]
	v_mfma_f32_16x16x32_bf16 v[78:81], v[114:117], v[170:173], v[78:81]
	v_mfma_f32_16x16x32_bf16 v[74:77], v[122:125], v[170:173], v[74:77]
	v_mfma_f32_16x16x32_bf16 v[166:169], v[118:121], v[134:137], v[166:169]
	v_mfma_f32_16x16x32_bf16 v[158:161], v[126:129], v[134:137], v[158:161]
	v_mfma_f32_16x16x32_bf16 v[110:113], v[118:121], v[142:145], v[110:113]
	v_mfma_f32_16x16x32_bf16 v[106:109], v[126:129], v[142:145], v[106:109]
	v_mfma_f32_16x16x32_bf16 v[94:97], v[118:121], v[162:165], v[94:97]
	v_mfma_f32_16x16x32_bf16 v[90:93], v[126:129], v[162:165], v[90:93]
	v_mfma_f32_16x16x32_bf16 v[78:81], v[118:121], v[174:177], v[78:81]
	v_mfma_f32_16x16x32_bf16 v[74:77], v[126:129], v[174:177], v[74:77]
	s_setprio 0
	s_barrier
	s_add_i32 s42, 0, 0x14000
	s_add_i32 s41, s41, s22
	v_add_u32_e32 v199, s42, v216
	v_lshl_add_u64 v[200:201], s[16:17], 0, v[0:1]
	s_mov_b32 m0, s41
	ds_read_b128 v[186:189], v199
	ds_read_b128 v[190:193], v199 offset:1024
	ds_read_b128 v[194:197], v199 offset:2048
	ds_read_b128 v[206:209], v199 offset:3072
	global_load_lds_dwordx4 v[200:201], off
	v_lshl_add_u64 v[220:221], s[16:17], 0, v[180:181]
	s_add_i32 m0, s41, 0x2000
	s_nop 0
	global_load_lds_dwordx4 v[220:221], off
	s_barrier
	s_waitcnt lgkmcnt(0)
	s_setprio 1
	s_waitcnt lgkmcnt(0)
	v_mfma_f32_16x16x32_bf16 v[150:153], v[186:189], v[130:133], v[150:153]
	v_mfma_f32_16x16x32_bf16 v[102:105], v[186:189], v[138:141], v[102:105]
	v_mfma_f32_16x16x32_bf16 v[98:101], v[194:197], v[138:141], v[98:101]
	v_mfma_f32_16x16x32_bf16 v[86:89], v[186:189], v[154:157], v[86:89]
	v_mfma_f32_16x16x32_bf16 v[82:85], v[194:197], v[154:157], v[82:85]
	v_mfma_f32_16x16x32_bf16 v[70:73], v[186:189], v[170:173], v[70:73]
	v_mfma_f32_16x16x32_bf16 v[66:69], v[194:197], v[170:173], v[66:69]
	v_mfma_f32_16x16x32_bf16 v[150:153], v[190:193], v[134:137], v[150:153]
	v_mfma_f32_16x16x32_bf16 v[130:133], v[194:197], v[130:133], v[146:149]
	v_mfma_f32_16x16x32_bf16 v[102:105], v[190:193], v[142:145], v[102:105]
	v_mfma_f32_16x16x32_bf16 v[98:101], v[206:209], v[142:145], v[98:101]
	v_mfma_f32_16x16x32_bf16 v[86:89], v[190:193], v[162:165], v[86:89]
	v_mfma_f32_16x16x32_bf16 v[82:85], v[206:209], v[162:165], v[82:85]
	v_mfma_f32_16x16x32_bf16 v[70:73], v[190:193], v[174:177], v[70:73]
	v_mfma_f32_16x16x32_bf16 v[66:69], v[206:209], v[174:177], v[66:69]
	v_mfma_f32_16x16x32_bf16 v[130:133], v[206:209], v[134:137], v[130:133]
	s_setprio 0
	s_mov_b32 m0, s23
	v_lshl_add_u64 v[222:223], s[14:15], 0, v[0:1]
	s_barrier
	ds_read_b128 v[134:137], v218 offset:16384
	ds_read_b128 v[138:141], v218 offset:17408
	ds_read_b128 v[142:145], v218 offset:18432
	ds_read_b128 v[146:149], v218 offset:19456
	ds_read_b128 v[154:157], v218 offset:20480
	ds_read_b128 v[162:165], v218 offset:21504
	ds_read_b128 v[170:173], v218 offset:22528
	ds_read_b128 v[174:177], v218 offset:23552
	global_load_lds_dwordx4 v[222:223], off
	v_lshl_add_u64 v[224:225], s[14:15], 0, v[180:181]
	s_mov_b32 m0, s24
	s_nop 0
	global_load_lds_dwordx4 v[224:225], off
	s_barrier
	s_waitcnt lgkmcnt(0)
	s_setprio 1
	s_waitcnt lgkmcnt(0)
	v_mfma_f32_16x16x32_bf16 v[62:65], v[114:117], v[134:137], v[62:65]
	v_mfma_f32_16x16x32_bf16 v[58:61], v[122:125], v[134:137], v[58:61]
	v_mfma_f32_16x16x32_bf16 v[46:49], v[114:117], v[142:145], v[46:49]
	v_mfma_f32_16x16x32_bf16 v[42:45], v[122:125], v[142:145], v[42:45]
	v_mfma_f32_16x16x32_bf16 v[30:33], v[114:117], v[154:157], v[30:33]
	v_mfma_f32_16x16x32_bf16 v[26:29], v[122:125], v[154:157], v[26:29]
	v_mfma_f32_16x16x32_bf16 v[14:17], v[114:117], v[170:173], v[14:17]
	v_mfma_f32_16x16x32_bf16 v[10:13], v[122:125], v[170:173], v[10:13]
	v_mfma_f32_16x16x32_bf16 v[62:65], v[118:121], v[138:141], v[62:65]
	v_mfma_f32_16x16x32_bf16 v[58:61], v[126:129], v[138:141], v[58:61]
	v_mfma_f32_16x16x32_bf16 v[46:49], v[118:121], v[146:149], v[46:49]
	v_mfma_f32_16x16x32_bf16 v[42:45], v[126:129], v[146:149], v[42:45]
	v_mfma_f32_16x16x32_bf16 v[30:33], v[118:121], v[162:165], v[30:33]
	v_mfma_f32_16x16x32_bf16 v[26:29], v[126:129], v[162:165], v[26:29]
	v_mfma_f32_16x16x32_bf16 v[14:17], v[118:121], v[174:177], v[14:17]
	v_mfma_f32_16x16x32_bf16 v[10:13], v[126:129], v[174:177], v[10:13]
	s_setprio 0
	s_barrier
	s_add_u32 s16, s16, s2
	s_addc_u32 s17, s17, 0
	s_add_i32 s41, s42, s22
	v_lshl_add_u64 v[226:227], s[16:17], 0, v[0:1]
	s_mov_b32 m0, s41
	v_lshl_add_u64 v[228:229], s[16:17], 0, v[180:181]
	global_load_lds_dwordx4 v[226:227], off
	s_add_i32 m0, s41, 0x2000
	s_nop 0
	global_load_lds_dwordx4 v[228:229], off
	s_waitcnt vmcnt(6)
	s_barrier
	s_setprio 1
	v_mfma_f32_16x16x32_bf16 v[54:57], v[186:189], v[134:137], v[54:57]
	v_mfma_f32_16x16x32_bf16 v[50:53], v[194:197], v[134:137], v[50:53]
	v_mfma_f32_16x16x32_bf16 v[38:41], v[186:189], v[142:145], v[38:41]
	v_mfma_f32_16x16x32_bf16 v[34:37], v[194:197], v[142:145], v[34:37]
	v_mfma_f32_16x16x32_bf16 v[22:25], v[186:189], v[154:157], v[22:25]
	v_mfma_f32_16x16x32_bf16 v[18:21], v[194:197], v[154:157], v[18:21]
	v_mfma_f32_16x16x32_bf16 v[6:9], v[186:189], v[170:173], v[6:9]
	v_mfma_f32_16x16x32_bf16 v[2:5], v[194:197], v[170:173], v[2:5]
	v_mfma_f32_16x16x32_bf16 v[54:57], v[190:193], v[138:141], v[54:57]
	v_mfma_f32_16x16x32_bf16 v[50:53], v[206:209], v[138:141], v[50:53]
	v_mfma_f32_16x16x32_bf16 v[38:41], v[190:193], v[146:149], v[38:41]
	v_mfma_f32_16x16x32_bf16 v[34:37], v[206:209], v[146:149], v[34:37]
	v_mfma_f32_16x16x32_bf16 v[22:25], v[190:193], v[162:165], v[22:25]
	v_mfma_f32_16x16x32_bf16 v[18:21], v[206:209], v[162:165], v[18:21]
	v_mfma_f32_16x16x32_bf16 v[6:9], v[190:193], v[174:177], v[6:9]
	v_mfma_f32_16x16x32_bf16 v[2:5], v[206:209], v[174:177], v[2:5]
	s_setprio 0
	s_add_i32 s16, 0, 0x18000
	v_add_u32_e32 v126, s16, v216
	s_barrier
	ds_read_b128 v[114:117], v126
	ds_read_b128 v[118:121], v126 offset:1024
	ds_read_b128 v[122:125], v126 offset:2048
	ds_read_b128 v[126:129], v126 offset:3072
	s_add_u32 s14, s14, s2
	s_addc_u32 s15, s15, 0
	s_mov_b32 m0, s25
	v_lshl_add_u64 v[146:147], s[14:15], 0, v[0:1]
	ds_read_b128 v[134:137], v218 offset:32768
	ds_read_b128 v[138:141], v218 offset:33792
	ds_read_b128 v[142:145], v218 offset:34816
	ds_read_b128 v[154:157], v218 offset:35840
	ds_read_b128 v[162:165], v218 offset:36864
	ds_read_b128 v[170:173], v218 offset:37888
	ds_read_b128 v[174:177], v218 offset:38912
	ds_read_b128 v[186:189], v218 offset:39936
	global_load_lds_dwordx4 v[146:147], off
	v_lshl_add_u64 v[146:147], s[14:15], 0, v[180:181]
	s_mov_b32 m0, s26
	s_nop 0
	global_load_lds_dwordx4 v[146:147], off
	s_waitcnt lgkmcnt(8)
	s_barrier
	s_waitcnt lgkmcnt(0)
	s_setprio 1
	s_waitcnt lgkmcnt(0)
	v_mfma_f32_16x16x32_bf16 v[146:149], v[114:117], v[134:137], v[166:169]
	v_mfma_f32_16x16x32_bf16 v[166:169], v[118:121], v[138:141], v[146:149]
	v_mfma_f32_16x16x32_bf16 v[146:149], v[122:125], v[134:137], v[158:161]
	v_mfma_f32_16x16x32_bf16 v[110:113], v[114:117], v[142:145], v[110:113]
	v_mfma_f32_16x16x32_bf16 v[106:109], v[122:125], v[142:145], v[106:109]
	v_mfma_f32_16x16x32_bf16 v[94:97], v[114:117], v[162:165], v[94:97]
	v_mfma_f32_16x16x32_bf16 v[90:93], v[122:125], v[162:165], v[90:93]
	v_mfma_f32_16x16x32_bf16 v[78:81], v[114:117], v[174:177], v[78:81]
	v_mfma_f32_16x16x32_bf16 v[74:77], v[122:125], v[174:177], v[74:77]
	v_mfma_f32_16x16x32_bf16 v[158:161], v[126:129], v[138:141], v[146:149]
	v_mfma_f32_16x16x32_bf16 v[110:113], v[118:121], v[154:157], v[110:113]
	v_mfma_f32_16x16x32_bf16 v[106:109], v[126:129], v[154:157], v[106:109]
	v_mfma_f32_16x16x32_bf16 v[94:97], v[118:121], v[170:173], v[94:97]
	v_mfma_f32_16x16x32_bf16 v[90:93], v[126:129], v[170:173], v[90:93]
	v_mfma_f32_16x16x32_bf16 v[78:81], v[118:121], v[186:189], v[78:81]
	v_mfma_f32_16x16x32_bf16 v[74:77], v[126:129], v[186:189], v[74:77]
	s_setprio 0
	s_barrier
	s_add_i32 s14, 0, 0x1c000
	v_add_u32_e32 v146, s14, v216
	s_add_i32 s15, s16, s22
	ds_read_b128 v[190:193], v146
	ds_read_b128 v[194:197], v146 offset:1024
	ds_read_b128 v[206:209], v146 offset:2048
	ds_read_b128 v[210:213], v146 offset:3072
	v_lshl_add_u64 v[146:147], v[200:201], 0, s[78:79]
	s_mov_b32 m0, s15
	s_nop 0
	global_load_lds_dwordx4 v[146:147], off
	v_lshl_add_u64 v[146:147], v[220:221], 0, s[78:79]
	s_add_i32 m0, s15, 0x2000
	s_nop 0
	global_load_lds_dwordx4 v[146:147], off
	s_barrier
	s_waitcnt lgkmcnt(0)
	s_setprio 1
	s_waitcnt lgkmcnt(0)
	v_mfma_f32_16x16x32_bf16 v[146:149], v[190:193], v[134:137], v[150:153]
	v_mfma_f32_16x16x32_bf16 v[130:133], v[206:209], v[134:137], v[130:133]
	v_mfma_f32_16x16x32_bf16 v[102:105], v[190:193], v[142:145], v[102:105]
	v_mfma_f32_16x16x32_bf16 v[98:101], v[206:209], v[142:145], v[98:101]
	v_mfma_f32_16x16x32_bf16 v[86:89], v[190:193], v[162:165], v[86:89]
	v_mfma_f32_16x16x32_bf16 v[82:85], v[206:209], v[162:165], v[82:85]
	v_mfma_f32_16x16x32_bf16 v[70:73], v[190:193], v[174:177], v[70:73]
	v_mfma_f32_16x16x32_bf16 v[66:69], v[206:209], v[174:177], v[66:69]
	v_mfma_f32_16x16x32_bf16 v[150:153], v[194:197], v[138:141], v[146:149]
	v_mfma_f32_16x16x32_bf16 v[146:149], v[210:213], v[138:141], v[130:133]
	v_mfma_f32_16x16x32_bf16 v[102:105], v[194:197], v[154:157], v[102:105]
	v_mfma_f32_16x16x32_bf16 v[98:101], v[210:213], v[154:157], v[98:101]
	v_mfma_f32_16x16x32_bf16 v[86:89], v[194:197], v[170:173], v[86:89]
	v_mfma_f32_16x16x32_bf16 v[82:85], v[210:213], v[170:173], v[82:85]
	v_mfma_f32_16x16x32_bf16 v[70:73], v[194:197], v[186:189], v[70:73]
	v_mfma_f32_16x16x32_bf16 v[66:69], v[210:213], v[186:189], v[66:69]
	s_setprio 0
	s_mov_b32 m0, s28
	v_lshl_add_u64 v[186:187], v[222:223], 0, s[78:79]
	s_barrier
	ds_read_b128 v[130:133], v218 offset:49152
	ds_read_b128 v[134:137], v218 offset:50176
	ds_read_b128 v[138:141], v218 offset:51200
	ds_read_b128 v[142:145], v218 offset:52224
	ds_read_b128 v[154:157], v218 offset:53248
	ds_read_b128 v[162:165], v218 offset:54272
	ds_read_b128 v[170:173], v218 offset:55296
	ds_read_b128 v[174:177], v218 offset:56320
	global_load_lds_dwordx4 v[186:187], off
	v_lshl_add_u64 v[186:187], v[224:225], 0, s[78:79]
	s_mov_b32 m0, s29
	s_nop 0
	global_load_lds_dwordx4 v[186:187], off
	s_barrier
	s_waitcnt lgkmcnt(0)
	s_setprio 1
	s_waitcnt lgkmcnt(0)
	v_mfma_f32_16x16x32_bf16 v[62:65], v[114:117], v[130:133], v[62:65]
	v_mfma_f32_16x16x32_bf16 v[58:61], v[122:125], v[130:133], v[58:61]
	v_mfma_f32_16x16x32_bf16 v[46:49], v[114:117], v[138:141], v[46:49]
	v_mfma_f32_16x16x32_bf16 v[42:45], v[122:125], v[138:141], v[42:45]
	v_mfma_f32_16x16x32_bf16 v[30:33], v[114:117], v[154:157], v[30:33]
	v_mfma_f32_16x16x32_bf16 v[26:29], v[122:125], v[154:157], v[26:29]
	v_mfma_f32_16x16x32_bf16 v[14:17], v[114:117], v[170:173], v[14:17]
	v_mfma_f32_16x16x32_bf16 v[10:13], v[122:125], v[170:173], v[10:13]
	v_mfma_f32_16x16x32_bf16 v[62:65], v[118:121], v[134:137], v[62:65]
	v_mfma_f32_16x16x32_bf16 v[58:61], v[126:129], v[134:137], v[58:61]
	v_mfma_f32_16x16x32_bf16 v[46:49], v[118:121], v[142:145], v[46:49]
	v_mfma_f32_16x16x32_bf16 v[42:45], v[126:129], v[142:145], v[42:45]
	v_mfma_f32_16x16x32_bf16 v[30:33], v[118:121], v[162:165], v[30:33]
	v_mfma_f32_16x16x32_bf16 v[26:29], v[126:129], v[162:165], v[26:29]
	v_mfma_f32_16x16x32_bf16 v[14:17], v[118:121], v[174:177], v[14:17]
	v_mfma_f32_16x16x32_bf16 v[10:13], v[126:129], v[174:177], v[10:13]
	s_setprio 0
	s_barrier
	s_add_i32 s14, s14, s22
	v_lshl_add_u64 v[114:115], v[226:227], 0, s[78:79]
	s_mov_b32 m0, s14
	s_nop 0
	global_load_lds_dwordx4 v[114:115], off
	v_lshl_add_u64 v[114:115], v[228:229], 0, s[78:79]
	s_add_i32 m0, s14, 0x2000
	s_nop 0
	global_load_lds_dwordx4 v[114:115], off
	s_waitcnt vmcnt(6)
	s_barrier
	s_setprio 1
	v_mfma_f32_16x16x32_bf16 v[54:57], v[190:193], v[130:133], v[54:57]
	v_mfma_f32_16x16x32_bf16 v[50:53], v[206:209], v[130:133], v[50:53]
	v_mfma_f32_16x16x32_bf16 v[38:41], v[190:193], v[138:141], v[38:41]
	v_mfma_f32_16x16x32_bf16 v[34:37], v[206:209], v[138:141], v[34:37]
	v_mfma_f32_16x16x32_bf16 v[22:25], v[190:193], v[154:157], v[22:25]
	v_mfma_f32_16x16x32_bf16 v[18:21], v[206:209], v[154:157], v[18:21]
	v_mfma_f32_16x16x32_bf16 v[6:9], v[190:193], v[170:173], v[6:9]
	v_mfma_f32_16x16x32_bf16 v[2:5], v[206:209], v[170:173], v[2:5]
	v_mfma_f32_16x16x32_bf16 v[54:57], v[194:197], v[134:137], v[54:57]
	v_mfma_f32_16x16x32_bf16 v[50:53], v[210:213], v[134:137], v[50:53]
	v_mfma_f32_16x16x32_bf16 v[38:41], v[194:197], v[142:145], v[38:41]
	v_mfma_f32_16x16x32_bf16 v[34:37], v[210:213], v[142:145], v[34:37]
	v_mfma_f32_16x16x32_bf16 v[22:25], v[194:197], v[162:165], v[22:25]
	v_mfma_f32_16x16x32_bf16 v[18:21], v[210:213], v[162:165], v[18:21]
	v_mfma_f32_16x16x32_bf16 v[6:9], v[194:197], v[174:177], v[6:9]
	v_mfma_f32_16x16x32_bf16 v[2:5], v[210:213], v[174:177], v[2:5]
	s_setprio 0
	s_add_u32 s12, s12, 0x100
	s_addc_u32 s13, s13, 0
	s_add_u32 s38, s38, 0x100
	s_addc_u32 s39, s39, 0
	s_cmp_ge_u32 s40, s27
	s_mov_b32 s14, s40
	s_barrier
	s_cbranch_scc0 .LBB0_1348
	v_readlane_b32 s100, v254, 20
	s_nop 1
	s_cmp_lg_u32 s100, 3
	s_cselect_b64 s[100:101], -1, 0
	s_and_b64 s[0:1], s[0:1], s[100:101]
	v_lshl_add_u32 v190, s37, 8, v179
	v_lshl_or_b32 v186, s36, 8, v217
	v_ashrrev_i32_e32 v187, 31, v186
	v_ashrrev_i32_e32 v191, 31, v190
	v_lshl_add_u64 v[188:189], v[186:187], 2, s[10:11]
	v_lshlrev_b64 v[114:115], 13, v[190:191]
	v_lshl_add_u64 v[114:115], v[188:189], 0, v[114:115]
	global_load_dwordx4 v[206:209], v[114:115], off
	global_load_dwordx4 v[210:213], v[114:115], off offset:64
	global_load_dwordx4 v[220:223], v[114:115], off offset:512
	global_load_dwordx4 v[224:227], v[114:115], off offset:576
	v_or_b32_e32 v196, 16, v190
	v_ashrrev_i32_e32 v197, 31, v196
	v_lshlrev_b64 v[114:115], 13, v[196:197]
	v_or_b32_e32 v194, 32, v190
	v_lshl_add_u64 v[114:115], v[188:189], 0, v[114:115]
	v_ashrrev_i32_e32 v195, 31, v194
	global_load_dwordx4 v[174:177], v[114:115], off
	global_load_dwordx4 v[170:173], v[114:115], off offset:64
	global_load_dwordx4 v[162:165], v[114:115], off offset:512
	global_load_dwordx4 v[154:157], v[114:115], off offset:576
	v_lshlrev_b64 v[114:115], 13, v[194:195]
	v_or_b32_e32 v192, 48, v190
	v_lshl_add_u64 v[114:115], v[188:189], 0, v[114:115]
	v_ashrrev_i32_e32 v193, 31, v192
	global_load_dwordx4 v[142:145], v[114:115], off
	global_load_dwordx4 v[138:141], v[114:115], off offset:64
	global_load_dwordx4 v[130:133], v[114:115], off offset:512
	global_load_dwordx4 v[122:125], v[114:115], off offset:576
	v_lshlrev_b64 v[114:115], 13, v[192:193]
	v_lshl_add_u64 v[114:115], v[188:189], 0, v[114:115]
	global_load_dwordx4 v[134:137], v[114:115], off
	global_load_dwordx4 v[126:129], v[114:115], off offset:64
	global_load_dwordx4 v[118:121], v[114:115], off offset:512
	s_nop 0
	global_load_dwordx4 v[114:117], v[114:115], off offset:576
	v_lshlrev_b64 v[200:201], 11, v[190:191]
	v_lshl_add_u64 v[200:201], v[200:201], 0, v[186:187]
	v_readlane_b32 s12, v252, 35
	v_readlane_b32 s13, v252, 36
	s_waitcnt vmcnt(0)
	v_pk_add_f32 v[166:167], v[166:167], v[206:207]
	s_nop 0
	v_mul_f32_e32 v199, v167, v167
	v_pk_add_f32 v[168:169], v[168:169], v[208:209]
	v_fmac_f32_e32 v199, v166, v166
	v_lshl_add_u64 v[206:207], v[200:201], 2, s[72:73]
	v_fmac_f32_e32 v199, v168, v168
	global_store_dwordx4 v[206:207], v[166:169], off
	v_fmac_f32_e32 v199, v169, v169
	v_pk_add_f32 v[158:159], v[158:159], v[210:211]
	v_cvt_pk_bf16_f32 v166, v166, v167
	v_cvt_pk_bf16_f32 v167, v168, v169
	v_lshlrev_b64 v[168:169], 1, v[200:201]
	v_lshl_add_u64 v[200:201], s[12:13], 0, v[168:169]
	s_mov_b64 exec, s[100:101]
	global_store_dwordx2 v[200:201], v[166:167], off
	s_mov_b64 exec, -1
	v_mul_f32_e32 v166, v159, v159
	v_pk_add_f32 v[160:161], v[160:161], v[212:213]
	v_fmac_f32_e32 v166, v158, v158
	v_fmac_f32_e32 v166, v160, v160
	global_store_dwordx4 v[206:207], v[158:161], off offset:64
	v_fmac_f32_e32 v166, v161, v161
	v_pk_add_f32 v[150:151], v[150:151], v[220:221]
	v_cvt_pk_bf16_f32 v158, v158, v159
	v_cvt_pk_bf16_f32 v159, v160, v161
	v_or_b32_e32 v160, 32, v168
	v_mov_b32_e32 v161, v169
	v_lshl_add_u64 v[160:161], s[12:13], 0, v[160:161]
	s_mov_b64 exec, s[100:101]
	global_store_dwordx2 v[160:161], v[158:159], off
	s_mov_b64 exec, -1
	v_mul_f32_e32 v158, v151, v151
	v_pk_add_f32 v[152:153], v[152:153], v[222:223]
	v_fmac_f32_e32 v158, v150, v150
	v_fmac_f32_e32 v158, v152, v152
	global_store_dwordx4 v[206:207], v[150:153], off offset:512
	v_fmac_f32_e32 v158, v153, v153
	v_pk_add_f32 v[146:147], v[146:147], v[224:225]
	v_cvt_pk_bf16_f32 v150, v150, v151
	v_cvt_pk_bf16_f32 v151, v152, v153
	v_or_b32_e32 v152, 0x100, v168
	v_mov_b32_e32 v153, v169
	v_lshl_add_u64 v[152:153], s[12:13], 0, v[152:153]
	s_mov_b64 exec, s[100:101]
	global_store_dwordx2 v[152:153], v[150:151], off
	s_mov_b64 exec, -1
	v_mul_f32_e32 v150, v147, v147
	v_pk_add_f32 v[148:149], v[148:149], v[226:227]
	v_fmac_f32_e32 v150, v146, v146
	v_fmac_f32_e32 v150, v148, v148
	v_or_b32_e32 v168, 0x120, v168
	global_store_dwordx4 v[206:207], v[146:149], off offset:576
	v_fmac_f32_e32 v150, v149, v149
	v_add_f32_e32 v166, v199, v166
	v_cvt_pk_bf16_f32 v146, v146, v147
	v_cvt_pk_bf16_f32 v147, v148, v149
	v_lshl_add_u64 v[148:149], s[12:13], 0, v[168:169]
	s_mov_b64 exec, s[100:101]
	global_store_dwordx2 v[148:149], v[146:147], off
	s_mov_b64 exec, -1
	v_and_b32_e32 v147, 64, v205
	v_xor_b32_e32 v146, 16, v205
	v_add_u32_e32 v147, 64, v147
	v_cmp_lt_i32_e32 vcc, v146, v147
	v_add_f32_e32 v158, v166, v158
	v_add_f32_e32 v150, v158, v150
	v_cndmask_b32_e32 v146, v205, v146, vcc
	v_lshlrev_b32_e32 v166, 2, v146
	ds_bpermute_b32 v146, v166, v150
	v_xor_b32_e32 v148, 32, v205
	v_cmp_lt_i32_e32 vcc, v148, v147
	s_waitcnt lgkmcnt(0)
	v_add_f32_e32 v146, v150, v146
	v_cndmask_b32_e32 v147, v205, v148, vcc
	v_lshlrev_b32_e32 v167, 2, v147
	ds_bpermute_b32 v147, v167, v146
	s_and_saveexec_b64 s[12:13], s[0:1]
	s_cbranch_execz .LBB0_1351
	v_readlane_b32 s14, v252, 28
	v_readlane_b32 s15, v252, 29
	s_waitcnt lgkmcnt(0)
	v_add_f32_e32 v146, v146, v147
	v_lshl_add_u64 v[148:149], v[190:191], 2, s[14:15]
	global_atomic_add_f32 v[148:149], v146, off
.LBB0_1351:
	s_or_b64 exec, exec, s[12:13]
	v_pk_add_f32 v[110:111], v[110:111], v[174:175]
	s_waitcnt lgkmcnt(0)
	v_lshlrev_b64 v[146:147], 11, v[196:197]
	v_mul_f32_e32 v150, v111, v111
	v_lshl_add_u64 v[146:147], v[146:147], 0, v[186:187]
	v_pk_add_f32 v[112:113], v[112:113], v[176:177]
	v_fmac_f32_e32 v150, v110, v110
	v_lshl_add_u64 v[148:149], v[146:147], 2, s[72:73]
	v_fmac_f32_e32 v150, v112, v112
	v_readlane_b32 s12, v252, 35
	global_store_dwordx4 v[148:149], v[110:113], off
	v_fmac_f32_e32 v150, v113, v113
	v_readlane_b32 s13, v252, 36
	v_cvt_pk_bf16_f32 v110, v110, v111
	v_cvt_pk_bf16_f32 v111, v112, v113
	v_lshlrev_b64 v[112:113], 1, v[146:147]
	v_pk_add_f32 v[106:107], v[106:107], v[170:171]
	v_lshl_add_u64 v[146:147], s[12:13], 0, v[112:113]
	s_mov_b64 exec, s[100:101]
	global_store_dwordx2 v[146:147], v[110:111], off
	s_mov_b64 exec, -1
	v_mul_f32_e32 v110, v107, v107
	v_pk_add_f32 v[108:109], v[108:109], v[172:173]
	v_fmac_f32_e32 v110, v106, v106
	v_fmac_f32_e32 v110, v108, v108
	global_store_dwordx4 v[148:149], v[106:109], off offset:64
	v_fmac_f32_e32 v110, v109, v109
	v_pk_add_f32 v[102:103], v[102:103], v[162:163]
	v_cvt_pk_bf16_f32 v106, v106, v107
	v_cvt_pk_bf16_f32 v107, v108, v109
	v_or_b32_e32 v108, 32, v112
	v_mov_b32_e32 v109, v113
	v_lshl_add_u64 v[108:109], s[12:13], 0, v[108:109]
	s_mov_b64 exec, s[100:101]
	global_store_dwordx2 v[108:109], v[106:107], off
	s_mov_b64 exec, -1
	v_mul_f32_e32 v106, v103, v103
	v_pk_add_f32 v[98:99], v[98:99], v[154:155]
	v_pk_add_f32 v[104:105], v[104:105], v[164:165]
	v_fmac_f32_e32 v106, v102, v102
	v_mul_f32_e32 v107, v99, v99
	v_fmac_f32_e32 v106, v104, v104
	v_pk_add_f32 v[100:101], v[100:101], v[156:157]
	v_fmac_f32_e32 v107, v98, v98
	v_add_f32_e32 v110, v150, v110
	v_fmac_f32_e32 v106, v105, v105
	v_fmac_f32_e32 v107, v100, v100
	v_add_f32_e32 v106, v110, v106
	v_fmac_f32_e32 v107, v101, v101
	v_add_f32_e32 v106, v106, v107
	ds_bpermute_b32 v107, v166, v106
	global_store_dwordx4 v[148:149], v[102:105], off offset:512
	s_nop 1
	v_cvt_pk_bf16_f32 v102, v102, v103
	v_cvt_pk_bf16_f32 v103, v104, v105
	v_or_b32_e32 v104, 0x100, v112
	v_mov_b32_e32 v105, v113
	v_lshl_add_u64 v[104:105], s[12:13], 0, v[104:105]
	s_mov_b64 exec, s[100:101]
	global_store_dwordx2 v[104:105], v[102:103], off
	s_mov_b64 exec, -1
	global_store_dwordx4 v[148:149], v[98:101], off offset:576
	v_cvt_pk_bf16_f32 v102, v98, v99
	v_or_b32_e32 v112, 0x120, v112
	v_cvt_pk_bf16_f32 v103, v100, v101
	s_waitcnt lgkmcnt(0)
	v_add_f32_e32 v98, v106, v107
	ds_bpermute_b32 v99, v167, v98
	v_lshl_add_u64 v[100:101], s[12:13], 0, v[112:113]
	s_mov_b64 exec, s[100:101]
	global_store_dwordx2 v[100:101], v[102:103], off
	s_mov_b64 exec, -1
	s_and_saveexec_b64 s[12:13], s[0:1]
	s_cbranch_execz .LBB0_1353
	v_readlane_b32 s14, v252, 28
	v_readlane_b32 s15, v252, 29
	s_waitcnt lgkmcnt(0)
	v_add_f32_e32 v98, v98, v99
	v_lshl_add_u64 v[100:101], v[196:197], 2, s[14:15]
	global_atomic_add_f32 v[100:101], v98, off
.LBB0_1353:
	s_or_b64 exec, exec, s[12:13]
	v_add_u32_e32 v164, 0x80, v190
	v_ashrrev_i32_e32 v165, 31, v164
	s_waitcnt lgkmcnt(0)
	v_lshlrev_b64 v[98:99], 13, v[164:165]
	v_add_u32_e32 v162, 0x90, v190
	v_lshl_add_u64 v[98:99], v[188:189], 0, v[98:99]
	v_ashrrev_i32_e32 v163, 31, v162
	global_load_dwordx4 v[158:161], v[98:99], off
	global_load_dwordx4 v[154:157], v[98:99], off offset:64
	global_load_dwordx4 v[150:153], v[98:99], off offset:512
	global_load_dwordx4 v[146:149], v[98:99], off offset:576
	v_lshlrev_b64 v[98:99], 13, v[162:163]
	v_lshl_add_u64 v[98:99], v[188:189], 0, v[98:99]
	global_load_dwordx4 v[110:113], v[98:99], off
	global_load_dwordx4 v[106:109], v[98:99], off offset:64
	global_load_dwordx4 v[102:105], v[98:99], off offset:512
	s_nop 0
	global_load_dwordx4 v[98:101], v[98:99], off offset:576
	v_pk_add_f32 v[94:95], v[94:95], v[142:143]
	v_lshlrev_b64 v[168:169], 11, v[194:195]
	v_mul_f32_e32 v170, v95, v95
	v_lshl_add_u64 v[168:169], v[168:169], 0, v[186:187]
	v_pk_add_f32 v[96:97], v[96:97], v[144:145]
	v_fmac_f32_e32 v170, v94, v94
	v_lshl_add_u64 v[142:143], v[168:169], 2, s[72:73]
	v_fmac_f32_e32 v170, v96, v96
	v_readlane_b32 s12, v252, 35
	global_store_dwordx4 v[142:143], v[94:97], off
	v_fmac_f32_e32 v170, v97, v97
	v_readlane_b32 s13, v252, 36
	v_cvt_pk_bf16_f32 v94, v94, v95
	v_cvt_pk_bf16_f32 v95, v96, v97
	v_lshlrev_b64 v[96:97], 1, v[168:169]
	v_pk_add_f32 v[90:91], v[90:91], v[138:139]
	v_lshl_add_u64 v[144:145], s[12:13], 0, v[96:97]
	s_mov_b64 exec, s[100:101]
	global_store_dwordx2 v[144:145], v[94:95], off
	s_mov_b64 exec, -1
	v_mul_f32_e32 v94, v91, v91
	v_pk_add_f32 v[92:93], v[92:93], v[140:141]
	v_fmac_f32_e32 v94, v90, v90
	v_fmac_f32_e32 v94, v92, v92
	global_store_dwordx4 v[142:143], v[90:93], off offset:64
	v_fmac_f32_e32 v94, v93, v93
	v_pk_add_f32 v[86:87], v[86:87], v[130:131]
	v_cvt_pk_bf16_f32 v90, v90, v91
	v_cvt_pk_bf16_f32 v91, v92, v93
	v_or_b32_e32 v92, 32, v96
	v_mov_b32_e32 v93, v97
	v_lshl_add_u64 v[92:93], s[12:13], 0, v[92:93]
	s_mov_b64 exec, s[100:101]
	global_store_dwordx2 v[92:93], v[90:91], off
	s_mov_b64 exec, -1
	v_mul_f32_e32 v90, v87, v87
	v_pk_add_f32 v[82:83], v[82:83], v[122:123]
	v_pk_add_f32 v[88:89], v[88:89], v[132:133]
	v_fmac_f32_e32 v90, v86, v86
	v_mul_f32_e32 v91, v83, v83
	v_fmac_f32_e32 v90, v88, v88
	v_pk_add_f32 v[84:85], v[84:85], v[124:125]
	v_fmac_f32_e32 v91, v82, v82
	v_add_f32_e32 v94, v170, v94
	v_fmac_f32_e32 v90, v89, v89
	v_fmac_f32_e32 v91, v84, v84
	v_add_f32_e32 v90, v94, v90
	v_fmac_f32_e32 v91, v85, v85
	v_add_f32_e32 v90, v90, v91
	ds_bpermute_b32 v91, v166, v90
	global_store_dwordx4 v[142:143], v[86:89], off offset:512
	s_nop 1
	v_cvt_pk_bf16_f32 v86, v86, v87
	v_cvt_pk_bf16_f32 v87, v88, v89
	v_or_b32_e32 v88, 0x100, v96
	v_mov_b32_e32 v89, v97
	v_lshl_add_u64 v[88:89], s[12:13], 0, v[88:89]
	s_mov_b64 exec, s[100:101]
	global_store_dwordx2 v[88:89], v[86:87], off
	s_mov_b64 exec, -1
	global_store_dwordx4 v[142:143], v[82:85], off offset:576
	v_cvt_pk_bf16_f32 v86, v82, v83
	v_or_b32_e32 v96, 0x120, v96
	v_cvt_pk_bf16_f32 v87, v84, v85
	s_waitcnt lgkmcnt(0)
	v_add_f32_e32 v82, v90, v91
	ds_bpermute_b32 v83, v167, v82
	v_lshl_add_u64 v[84:85], s[12:13], 0, v[96:97]
	s_mov_b64 exec, s[100:101]
	global_store_dwordx2 v[84:85], v[86:87], off
	s_mov_b64 exec, -1
	s_and_saveexec_b64 s[12:13], s[0:1]
	s_cbranch_execz .LBB0_1355
	v_readlane_b32 s14, v252, 28
	v_readlane_b32 s15, v252, 29
	s_waitcnt lgkmcnt(0)
	v_add_f32_e32 v82, v82, v83
	v_lshl_add_u64 v[84:85], v[194:195], 2, s[14:15]
	global_atomic_add_f32 v[84:85], v82, off
.LBB0_1355:
	s_or_b64 exec, exec, s[12:13]
	v_pk_add_f32 v[78:79], v[78:79], v[134:135]
	s_waitcnt lgkmcnt(0)
	v_lshlrev_b64 v[82:83], 11, v[192:193]
	v_mul_f32_e32 v86, v79, v79
	v_lshl_add_u64 v[82:83], v[82:83], 0, v[186:187]
	v_pk_add_f32 v[80:81], v[80:81], v[136:137]
	v_fmac_f32_e32 v86, v78, v78
	v_lshl_add_u64 v[84:85], v[82:83], 2, s[72:73]
	v_fmac_f32_e32 v86, v80, v80
	v_readlane_b32 s12, v252, 35
	global_store_dwordx4 v[84:85], v[78:81], off
	v_fmac_f32_e32 v86, v81, v81
	v_readlane_b32 s13, v252, 36
	v_cvt_pk_bf16_f32 v78, v78, v79
	v_cvt_pk_bf16_f32 v79, v80, v81
	v_lshlrev_b64 v[80:81], 1, v[82:83]
	v_pk_add_f32 v[74:75], v[74:75], v[126:127]
	v_lshl_add_u64 v[82:83], s[12:13], 0, v[80:81]
	s_mov_b64 exec, s[100:101]
	global_store_dwordx2 v[82:83], v[78:79], off
	s_mov_b64 exec, -1
	v_mul_f32_e32 v78, v75, v75
	v_pk_add_f32 v[76:77], v[76:77], v[128:129]
	v_fmac_f32_e32 v78, v74, v74
	v_fmac_f32_e32 v78, v76, v76
	global_store_dwordx4 v[84:85], v[74:77], off offset:64
	v_fmac_f32_e32 v78, v77, v77
	v_pk_add_f32 v[70:71], v[70:71], v[118:119]
	v_cvt_pk_bf16_f32 v74, v74, v75
	v_cvt_pk_bf16_f32 v75, v76, v77
	v_or_b32_e32 v76, 32, v80
	v_mov_b32_e32 v77, v81
	v_lshl_add_u64 v[76:77], s[12:13], 0, v[76:77]
	s_mov_b64 exec, s[100:101]
	global_store_dwordx2 v[76:77], v[74:75], off
	s_mov_b64 exec, -1
	v_mul_f32_e32 v74, v71, v71
	v_pk_add_f32 v[66:67], v[66:67], v[114:115]
	v_pk_add_f32 v[72:73], v[72:73], v[120:121]
	v_fmac_f32_e32 v74, v70, v70
	v_mul_f32_e32 v75, v67, v67
	v_fmac_f32_e32 v74, v72, v72
	v_pk_add_f32 v[68:69], v[68:69], v[116:117]
	v_fmac_f32_e32 v75, v66, v66
	v_add_f32_e32 v78, v86, v78
	v_fmac_f32_e32 v74, v73, v73
	v_fmac_f32_e32 v75, v68, v68
	v_add_f32_e32 v74, v78, v74
	v_fmac_f32_e32 v75, v69, v69
	v_add_f32_e32 v74, v74, v75
	ds_bpermute_b32 v75, v166, v74
	global_store_dwordx4 v[84:85], v[70:73], off offset:512
	s_nop 1
	v_cvt_pk_bf16_f32 v70, v70, v71
	v_cvt_pk_bf16_f32 v71, v72, v73
	v_or_b32_e32 v72, 0x100, v80
	v_mov_b32_e32 v73, v81
	v_lshl_add_u64 v[72:73], s[12:13], 0, v[72:73]
	s_mov_b64 exec, s[100:101]
	global_store_dwordx2 v[72:73], v[70:71], off
	s_mov_b64 exec, -1
	global_store_dwordx4 v[84:85], v[66:69], off offset:576
	v_cvt_pk_bf16_f32 v70, v66, v67
	v_or_b32_e32 v80, 0x120, v80
	v_cvt_pk_bf16_f32 v71, v68, v69
	s_waitcnt lgkmcnt(0)
	v_add_f32_e32 v66, v74, v75
	ds_bpermute_b32 v67, v167, v66
	v_lshl_add_u64 v[68:69], s[12:13], 0, v[80:81]
	s_mov_b64 exec, s[100:101]
	global_store_dwordx2 v[68:69], v[70:71], off
	s_mov_b64 exec, -1
	s_and_saveexec_b64 s[12:13], s[0:1]
	s_cbranch_execz .LBB0_1357
	v_readlane_b32 s14, v252, 28
	v_readlane_b32 s15, v252, 29
	s_waitcnt lgkmcnt(0)
	v_add_f32_e32 v66, v66, v67
	v_lshl_add_u64 v[68:69], v[192:193], 2, s[14:15]
	global_atomic_add_f32 v[68:69], v66, off
.LBB0_1357:
	s_or_b64 exec, exec, s[12:13]
	v_add_u32_e32 v116, 0xa0, v190
	v_ashrrev_i32_e32 v117, 31, v116
	s_waitcnt lgkmcnt(0)
	v_lshlrev_b64 v[66:67], 13, v[116:117]
	v_add_u32_e32 v114, 0xb0, v190
	v_lshl_add_u64 v[66:67], v[188:189], 0, v[66:67]
	v_ashrrev_i32_e32 v115, 31, v114
	global_load_dwordx4 v[94:97], v[66:67], off
	global_load_dwordx4 v[90:93], v[66:67], off offset:64
	global_load_dwordx4 v[86:89], v[66:67], off offset:512
	global_load_dwordx4 v[82:85], v[66:67], off offset:576
	v_lshlrev_b64 v[66:67], 13, v[114:115]
	v_lshl_add_u64 v[66:67], v[188:189], 0, v[66:67]
	global_load_dwordx4 v[78:81], v[66:67], off
	global_load_dwordx4 v[74:77], v[66:67], off offset:64
	global_load_dwordx4 v[70:73], v[66:67], off offset:512
	s_nop 0
	global_load_dwordx4 v[66:69], v[66:67], off offset:576
	s_waitcnt vmcnt(31)
	v_pk_add_f32 v[62:63], v[62:63], v[158:159]
	v_lshlrev_b64 v[118:119], 11, v[164:165]
	v_mul_f32_e32 v122, v63, v63
	v_lshl_add_u64 v[118:119], v[118:119], 0, v[186:187]
	v_pk_add_f32 v[64:65], v[64:65], v[160:161]
	v_fmac_f32_e32 v122, v62, v62
	v_lshl_add_u64 v[120:121], v[118:119], 2, s[72:73]
	v_fmac_f32_e32 v122, v64, v64
	v_readlane_b32 s12, v252, 35
	global_store_dwordx4 v[120:121], v[62:65], off
	v_fmac_f32_e32 v122, v65, v65
	v_readlane_b32 s13, v252, 36
	v_cvt_pk_bf16_f32 v62, v62, v63
	v_cvt_pk_bf16_f32 v63, v64, v65
	v_lshlrev_b64 v[64:65], 1, v[118:119]
	s_waitcnt vmcnt(31)
	v_pk_add_f32 v[58:59], v[58:59], v[154:155]
	v_lshl_add_u64 v[118:119], s[12:13], 0, v[64:65]
	s_mov_b64 exec, s[100:101]
	global_store_dwordx2 v[118:119], v[62:63], off
	s_mov_b64 exec, -1
	v_mul_f32_e32 v62, v59, v59
	v_pk_add_f32 v[60:61], v[60:61], v[156:157]
	v_fmac_f32_e32 v62, v58, v58
	v_fmac_f32_e32 v62, v60, v60
	global_store_dwordx4 v[120:121], v[58:61], off offset:64
	v_fmac_f32_e32 v62, v61, v61
	s_waitcnt vmcnt(32)
	v_pk_add_f32 v[54:55], v[54:55], v[150:151]
	v_cvt_pk_bf16_f32 v58, v58, v59
	v_cvt_pk_bf16_f32 v59, v60, v61
	v_or_b32_e32 v60, 32, v64
	v_mov_b32_e32 v61, v65
	v_lshl_add_u64 v[60:61], s[12:13], 0, v[60:61]
	s_mov_b64 exec, s[100:101]
	global_store_dwordx2 v[60:61], v[58:59], off
	s_mov_b64 exec, -1
	v_mul_f32_e32 v58, v55, v55
	s_waitcnt vmcnt(32)
	v_pk_add_f32 v[50:51], v[50:51], v[146:147]
	v_pk_add_f32 v[56:57], v[56:57], v[152:153]
	v_fmac_f32_e32 v58, v54, v54
	v_mul_f32_e32 v59, v51, v51
	v_fmac_f32_e32 v58, v56, v56
	v_pk_add_f32 v[52:53], v[52:53], v[148:149]
	v_fmac_f32_e32 v59, v50, v50
	v_add_f32_e32 v62, v122, v62
	v_fmac_f32_e32 v58, v57, v57
	v_fmac_f32_e32 v59, v52, v52
	v_add_f32_e32 v58, v62, v58
	v_fmac_f32_e32 v59, v53, v53
	v_add_f32_e32 v58, v58, v59
	ds_bpermute_b32 v59, v166, v58
	global_store_dwordx4 v[120:121], v[54:57], off offset:512
	s_nop 1
	v_cvt_pk_bf16_f32 v54, v54, v55
	v_cvt_pk_bf16_f32 v55, v56, v57
	v_or_b32_e32 v56, 0x100, v64
	v_mov_b32_e32 v57, v65
	v_lshl_add_u64 v[56:57], s[12:13], 0, v[56:57]
	s_mov_b64 exec, s[100:101]
	global_store_dwordx2 v[56:57], v[54:55], off
	s_mov_b64 exec, -1
	global_store_dwordx4 v[120:121], v[50:53], off offset:576
	v_cvt_pk_bf16_f32 v54, v50, v51
	v_or_b32_e32 v64, 0x120, v64
	v_cvt_pk_bf16_f32 v55, v52, v53
	s_waitcnt lgkmcnt(0)
	v_add_f32_e32 v50, v58, v59
	ds_bpermute_b32 v51, v167, v50
	v_lshl_add_u64 v[52:53], s[12:13], 0, v[64:65]
	s_mov_b64 exec, s[100:101]
	global_store_dwordx2 v[52:53], v[54:55], off
	s_mov_b64 exec, -1
	s_and_saveexec_b64 s[12:13], s[0:1]
	s_cbranch_execz .LBB0_1359
	v_readlane_b32 s14, v252, 28
	v_readlane_b32 s15, v252, 29
	s_waitcnt lgkmcnt(0)
	v_add_f32_e32 v50, v50, v51
	v_lshl_add_u64 v[52:53], v[164:165], 2, s[14:15]
	global_atomic_add_f32 v[52:53], v50, off
.LBB0_1359:
	s_or_b64 exec, exec, s[12:13]
	s_waitcnt vmcnt(35)
	v_pk_add_f32 v[46:47], v[46:47], v[110:111]
	s_waitcnt lgkmcnt(0)
	v_lshlrev_b64 v[50:51], 11, v[162:163]
	v_mul_f32_e32 v54, v47, v47
	v_lshl_add_u64 v[50:51], v[50:51], 0, v[186:187]
	v_pk_add_f32 v[48:49], v[48:49], v[112:113]
	v_fmac_f32_e32 v54, v46, v46
	v_lshl_add_u64 v[52:53], v[50:51], 2, s[72:73]
	v_fmac_f32_e32 v54, v48, v48
	v_readlane_b32 s12, v252, 35
	global_store_dwordx4 v[52:53], v[46:49], off
	v_fmac_f32_e32 v54, v49, v49
	v_readlane_b32 s13, v252, 36
	v_cvt_pk_bf16_f32 v46, v46, v47
	v_cvt_pk_bf16_f32 v47, v48, v49
	v_lshlrev_b64 v[48:49], 1, v[50:51]
	s_waitcnt vmcnt(35)
	v_pk_add_f32 v[42:43], v[42:43], v[106:107]
	v_lshl_add_u64 v[50:51], s[12:13], 0, v[48:49]
	s_mov_b64 exec, s[100:101]
	global_store_dwordx2 v[50:51], v[46:47], off
	s_mov_b64 exec, -1
	v_mul_f32_e32 v46, v43, v43
	v_pk_add_f32 v[44:45], v[44:45], v[108:109]
	v_fmac_f32_e32 v46, v42, v42
	v_fmac_f32_e32 v46, v44, v44
	global_store_dwordx4 v[52:53], v[42:45], off offset:64
	v_fmac_f32_e32 v46, v45, v45
	s_waitcnt vmcnt(36)
	v_pk_add_f32 v[38:39], v[38:39], v[102:103]
	v_cvt_pk_bf16_f32 v42, v42, v43
	v_cvt_pk_bf16_f32 v43, v44, v45
	v_or_b32_e32 v44, 32, v48
	v_mov_b32_e32 v45, v49
	v_lshl_add_u64 v[44:45], s[12:13], 0, v[44:45]
	s_mov_b64 exec, s[100:101]
	global_store_dwordx2 v[44:45], v[42:43], off
	s_mov_b64 exec, -1
	v_mul_f32_e32 v42, v39, v39
	s_waitcnt vmcnt(36)
	v_pk_add_f32 v[34:35], v[34:35], v[98:99]
	v_pk_add_f32 v[40:41], v[40:41], v[104:105]
	v_fmac_f32_e32 v42, v38, v38
	v_mul_f32_e32 v43, v35, v35
	v_fmac_f32_e32 v42, v40, v40
	v_pk_add_f32 v[36:37], v[36:37], v[100:101]
	v_fmac_f32_e32 v43, v34, v34
	v_add_f32_e32 v46, v54, v46
	v_fmac_f32_e32 v42, v41, v41
	v_fmac_f32_e32 v43, v36, v36
	v_add_f32_e32 v42, v46, v42
	v_fmac_f32_e32 v43, v37, v37
	v_add_f32_e32 v42, v42, v43
	ds_bpermute_b32 v43, v166, v42
	global_store_dwordx4 v[52:53], v[38:41], off offset:512
	s_nop 1
	v_cvt_pk_bf16_f32 v38, v38, v39
	v_cvt_pk_bf16_f32 v39, v40, v41
	v_or_b32_e32 v40, 0x100, v48
	v_mov_b32_e32 v41, v49
	v_lshl_add_u64 v[40:41], s[12:13], 0, v[40:41]
	s_mov_b64 exec, s[100:101]
	global_store_dwordx2 v[40:41], v[38:39], off
	s_mov_b64 exec, -1
	global_store_dwordx4 v[52:53], v[34:37], off offset:576
	v_cvt_pk_bf16_f32 v38, v34, v35
	v_or_b32_e32 v48, 0x120, v48
	v_cvt_pk_bf16_f32 v39, v36, v37
	s_waitcnt lgkmcnt(0)
	v_add_f32_e32 v34, v42, v43
	ds_bpermute_b32 v35, v167, v34
	v_lshl_add_u64 v[36:37], s[12:13], 0, v[48:49]
	s_mov_b64 exec, s[100:101]
	global_store_dwordx2 v[36:37], v[38:39], off
	s_mov_b64 exec, -1
	s_and_saveexec_b64 s[12:13], s[0:1]
	s_cbranch_execz .LBB0_1361
	v_readlane_b32 s14, v252, 28
	v_readlane_b32 s15, v252, 29
	s_waitcnt lgkmcnt(0)
	v_add_f32_e32 v34, v34, v35
	v_lshl_add_u64 v[36:37], v[162:163], 2, s[14:15]
	global_atomic_add_f32 v[36:37], v34, off
.LBB0_1361:
	s_or_b64 exec, exec, s[12:13]
	s_waitcnt vmcnt(23)
	v_pk_add_f32 v[30:31], v[30:31], v[94:95]
	s_waitcnt lgkmcnt(0)
	v_lshlrev_b64 v[34:35], 11, v[116:117]
	v_mul_f32_e32 v38, v31, v31
	v_lshl_add_u64 v[34:35], v[34:35], 0, v[186:187]
	v_pk_add_f32 v[32:33], v[32:33], v[96:97]
	v_fmac_f32_e32 v38, v30, v30
	v_lshl_add_u64 v[36:37], v[34:35], 2, s[72:73]
	v_fmac_f32_e32 v38, v32, v32
	v_readlane_b32 s12, v252, 35
	global_store_dwordx4 v[36:37], v[30:33], off
	v_fmac_f32_e32 v38, v33, v33
	v_readlane_b32 s13, v252, 36
	v_cvt_pk_bf16_f32 v30, v30, v31
	v_cvt_pk_bf16_f32 v31, v32, v33
	v_lshlrev_b64 v[32:33], 1, v[34:35]
	s_waitcnt vmcnt(23)
	v_pk_add_f32 v[26:27], v[26:27], v[90:91]
	v_lshl_add_u64 v[34:35], s[12:13], 0, v[32:33]
	s_mov_b64 exec, s[100:101]
	global_store_dwordx2 v[34:35], v[30:31], off
	s_mov_b64 exec, -1
	v_mul_f32_e32 v30, v27, v27
	v_pk_add_f32 v[28:29], v[28:29], v[92:93]
	v_fmac_f32_e32 v30, v26, v26
	v_fmac_f32_e32 v30, v28, v28
	global_store_dwordx4 v[36:37], v[26:29], off offset:64
	v_fmac_f32_e32 v30, v29, v29
	s_waitcnt vmcnt(24)
	v_pk_add_f32 v[22:23], v[22:23], v[86:87]
	v_cvt_pk_bf16_f32 v26, v26, v27
	v_cvt_pk_bf16_f32 v27, v28, v29
	v_or_b32_e32 v28, 32, v32
	v_mov_b32_e32 v29, v33
	v_lshl_add_u64 v[28:29], s[12:13], 0, v[28:29]
	s_mov_b64 exec, s[100:101]
	global_store_dwordx2 v[28:29], v[26:27], off
	s_mov_b64 exec, -1
	v_mul_f32_e32 v26, v23, v23
	s_waitcnt vmcnt(24)
	v_pk_add_f32 v[18:19], v[18:19], v[82:83]
	v_pk_add_f32 v[24:25], v[24:25], v[88:89]
	v_fmac_f32_e32 v26, v22, v22
	v_mul_f32_e32 v27, v19, v19
	v_fmac_f32_e32 v26, v24, v24
	v_pk_add_f32 v[20:21], v[20:21], v[84:85]
	v_fmac_f32_e32 v27, v18, v18
	v_add_f32_e32 v30, v38, v30
	v_fmac_f32_e32 v26, v25, v25
	v_fmac_f32_e32 v27, v20, v20
	v_add_f32_e32 v26, v30, v26
	v_fmac_f32_e32 v27, v21, v21
	v_add_f32_e32 v26, v26, v27
	ds_bpermute_b32 v27, v166, v26
	global_store_dwordx4 v[36:37], v[22:25], off offset:512
	s_nop 1
	v_cvt_pk_bf16_f32 v22, v22, v23
	v_cvt_pk_bf16_f32 v23, v24, v25
	v_or_b32_e32 v24, 0x100, v32
	v_mov_b32_e32 v25, v33
	v_lshl_add_u64 v[24:25], s[12:13], 0, v[24:25]
	s_mov_b64 exec, s[100:101]
	global_store_dwordx2 v[24:25], v[22:23], off
	s_mov_b64 exec, -1
	global_store_dwordx4 v[36:37], v[18:21], off offset:576
	v_cvt_pk_bf16_f32 v22, v18, v19
	v_or_b32_e32 v32, 0x120, v32
	v_cvt_pk_bf16_f32 v23, v20, v21
	s_waitcnt lgkmcnt(0)
	v_add_f32_e32 v18, v26, v27
	ds_bpermute_b32 v19, v167, v18
	v_lshl_add_u64 v[20:21], s[12:13], 0, v[32:33]
	s_mov_b64 exec, s[100:101]
	global_store_dwordx2 v[20:21], v[22:23], off
	s_mov_b64 exec, -1
	s_and_saveexec_b64 s[12:13], s[0:1]
	s_cbranch_execz .LBB0_1363
	v_readlane_b32 s14, v252, 28
	v_readlane_b32 s15, v252, 29
	s_waitcnt lgkmcnt(0)
	v_add_f32_e32 v18, v18, v19
	v_lshl_add_u64 v[20:21], v[116:117], 2, s[14:15]
	global_atomic_add_f32 v[20:21], v18, off
.LBB0_1363:
	s_or_b64 exec, exec, s[12:13]
	s_waitcnt vmcnt(27)
	v_pk_add_f32 v[14:15], v[14:15], v[78:79]
	s_waitcnt lgkmcnt(0)
	v_lshlrev_b64 v[18:19], 11, v[114:115]
	v_mul_f32_e32 v22, v15, v15
	v_lshl_add_u64 v[18:19], v[18:19], 0, v[186:187]
	v_pk_add_f32 v[16:17], v[16:17], v[80:81]
	v_fmac_f32_e32 v22, v14, v14
	v_lshl_add_u64 v[20:21], v[18:19], 2, s[72:73]
	v_fmac_f32_e32 v22, v16, v16
	v_readlane_b32 s12, v252, 35
	global_store_dwordx4 v[20:21], v[14:17], off
	v_fmac_f32_e32 v22, v17, v17
	v_readlane_b32 s13, v252, 36
	v_cvt_pk_bf16_f32 v14, v14, v15
	v_cvt_pk_bf16_f32 v15, v16, v17
	v_lshlrev_b64 v[16:17], 1, v[18:19]
	s_waitcnt vmcnt(27)
	v_pk_add_f32 v[10:11], v[10:11], v[74:75]
	v_lshl_add_u64 v[18:19], s[12:13], 0, v[16:17]
	s_mov_b64 exec, s[100:101]
	global_store_dwordx2 v[18:19], v[14:15], off
	s_mov_b64 exec, -1
	v_mul_f32_e32 v14, v11, v11
	v_pk_add_f32 v[12:13], v[12:13], v[76:77]
	v_fmac_f32_e32 v14, v10, v10
	v_fmac_f32_e32 v14, v12, v12
	global_store_dwordx4 v[20:21], v[10:13], off offset:64
	v_fmac_f32_e32 v14, v13, v13
	s_waitcnt vmcnt(28)
	v_pk_add_f32 v[6:7], v[6:7], v[70:71]
	v_cvt_pk_bf16_f32 v10, v10, v11
	v_cvt_pk_bf16_f32 v11, v12, v13
	v_or_b32_e32 v12, 32, v16
	v_mov_b32_e32 v13, v17
	v_lshl_add_u64 v[12:13], s[12:13], 0, v[12:13]
	s_mov_b64 exec, s[100:101]
	global_store_dwordx2 v[12:13], v[10:11], off
	s_mov_b64 exec, -1
	v_mul_f32_e32 v10, v7, v7
	s_waitcnt vmcnt(28)
	v_pk_add_f32 v[2:3], v[2:3], v[66:67]
	v_pk_add_f32 v[8:9], v[8:9], v[72:73]
	v_fmac_f32_e32 v10, v6, v6
	v_mul_f32_e32 v11, v3, v3
	v_fmac_f32_e32 v10, v8, v8
	v_pk_add_f32 v[4:5], v[4:5], v[68:69]
	v_fmac_f32_e32 v11, v2, v2
	v_add_f32_e32 v14, v22, v14
	v_fmac_f32_e32 v10, v9, v9
	v_fmac_f32_e32 v11, v4, v4
	v_add_f32_e32 v10, v14, v10
	v_fmac_f32_e32 v11, v5, v5
	v_add_f32_e32 v10, v10, v11
	ds_bpermute_b32 v11, v166, v10
	global_store_dwordx4 v[20:21], v[6:9], off offset:512
	s_nop 1
	v_cvt_pk_bf16_f32 v6, v6, v7
	v_cvt_pk_bf16_f32 v7, v8, v9
	v_or_b32_e32 v8, 0x100, v16
	v_mov_b32_e32 v9, v17
	v_lshl_add_u64 v[8:9], s[12:13], 0, v[8:9]
	s_mov_b64 exec, s[100:101]
	global_store_dwordx2 v[8:9], v[6:7], off
	s_mov_b64 exec, -1
	global_store_dwordx4 v[20:21], v[2:5], off offset:576
	v_cvt_pk_bf16_f32 v6, v2, v3
	v_or_b32_e32 v16, 0x120, v16
	v_cvt_pk_bf16_f32 v7, v4, v5
	s_waitcnt lgkmcnt(0)
	v_add_f32_e32 v2, v10, v11
	ds_bpermute_b32 v3, v167, v2
	v_lshl_add_u64 v[4:5], s[12:13], 0, v[16:17]
	s_mov_b64 exec, s[100:101]
	global_store_dwordx2 v[4:5], v[6:7], off
	s_mov_b64 exec, -1
	s_and_saveexec_b64 s[12:13], s[0:1]
	s_cbranch_execz .LBB0_1336
	v_readlane_b32 s14, v252, 28
	v_readlane_b32 s15, v252, 29
	s_waitcnt lgkmcnt(0)
	v_add_f32_e32 v2, v2, v3
	v_lshl_add_u64 v[4:5], v[114:115], 2, s[14:15]
	global_atomic_add_f32 v[4:5], v2, off
	s_branch .LBB0_1336
